# bg queues skipped by the workgroups that finish last; up-GEMM partial 5th round split into 64 half-units (rows 128h.. of the tile) with a K-loop copy without the other half's MFMAs
# speedup vs baseline: 1.0740x; 1.0079x over previous
.LBB0_767:
	v_readlane_b32 s12, v254, 0
	s_cmpk_lt_u32 s12, 0xc0
	s_cbranch_scc1 .LBB0_798
	s_and_saveexec_b64 s[12:13], s[4:5]
	s_cbranch_execz .LBB0_771
	s_mov_b64 s[16:17], exec
	v_mbcnt_lo_u32_b32 v0, s16, 0
	v_mbcnt_hi_u32_b32 v0, s17, v0
	v_cmp_eq_u32_e32 vcc, 0, v0
	s_and_saveexec_b64 s[14:15], vcc
	s_cbranch_execz .LBB0_770
	s_bcnt1_i32_b64 s16, s[16:17]
	v_mov_b32_e32 v1, s16
	global_atomic_add v1, v169, v1, s[0:1] sc0

.LBB0_875:
	s_add_u32 s16, s25, 0x2f82000
	s_addc_u32 s17, s24, 0
	s_add_u32 s18, s25, 0x7182000
	v_readlane_b32 s1, v254, 53
	s_addc_u32 s19, s24, 0
	s_mul_i32 s1, s1, 0x10800
	s_add_u32 s20, s13, s1
	s_addc_u32 s21, s7, 0
	s_lshl_b32 s1, s12, 2
	s_add_u32 s1, s25, s1
	s_addc_u32 s7, s24, 0
	s_add_u32 s22, s1, 0x2efe000
	s_addc_u32 s23, s7, 0
	s_lshl_b32 s1, s6, 2
	s_add_u32 s1, s25, s1
	s_addc_u32 s6, s24, 0
	v_bfe_u32 v236, v12, 4, 2
	s_add_u32 s58, s1, 0x2f3d000
	v_and_b32_e32 v235, 15, v12
	v_lshlrev_b32_e32 v15, 4, v236
	v_lshlrev_b32_e32 v12, 2, v12
	s_addc_u32 s59, s6, 0
	v_lshl_or_b32 v15, v235, 6, v15
	s_lshl_b32 s1, s14, 13
	v_and_b32_e32 v12, 32, v12
	v_bitop3_b32 v16, v15, s1, v12 bitop3:0xde
	s_lshl_b32 s1, s15, 5
	s_and_b32 s61, s1, 0x60
	s_add_i32 m0, s54, 0x18000
	v_lshl_add_u64 v[6:7], v[6:7], 0, s[78:79]
	s_lshl_b32 s60, s14, 6
	s_lshl_b32 s1, s61, 7
	s_waitcnt vmcnt(4)
	s_barrier
	global_load_lds_dwordx4 v[6:7], off
	v_lshl_add_u64 v[4:5], v[4:5], 0, s[78:79]
	s_add_i32 m0, s54, 0x1a000
	s_add_i32 s62, s54, 0x8000
	s_add_i32 s63, s54, 0xa000
	global_load_lds_dwordx4 v[4:5], off
	v_lshl_add_u64 v[2:3], v[2:3], 0, s[78:79]
	s_mov_b32 m0, s62
	s_add_u32 s6, s2, 0x40080
	global_load_lds_dwordx4 v[2:3], off
	v_lshl_add_u64 v[0:1], v[0:1], 0, s[78:79]
	s_mov_b32 m0, s63
	s_addc_u32 s7, s3, 0
	global_load_lds_dwordx4 v[0:1], off
	s_add_i32 m0, s54, 0x1c000
	v_lshl_add_u64 v[0:1], s[6:7], 0, v[168:169]
	global_load_lds_dwordx4 v[0:1], off
	v_lshl_add_u64 v[0:1], s[6:7], 0, v[184:185]
	s_add_i32 m0, s54, 0x1e000
	s_ashr_i32 s64, s45, 31
	global_load_lds_dwordx4 v[0:1], off
	s_add_u32 s24, s20, 0x2c00
	s_addc_u32 s25, s21, 0
	v_lshlrev_b32_e32 v0, 14, v8
	s_add_u32 s26, s20, 0x5800
	v_and_b32_e32 v0, 0xffff8000, v0
	s_addc_u32 s27, s21, 0
	v_lshl_add_u32 v0, v9, 11, v0
	v_and_b32_e32 v1, 1, v8
	s_add_u32 s28, s20, 0x8400
	v_lshl_or_b32 v0, v1, 6, v0
	s_addc_u32 s29, s21, 0
	v_lshl_add_u32 v186, v10, 1, v0
	v_lshlrev_b32_e32 v0, 14, v11
	s_add_u32 s30, s20, 0xb000
	v_and_b32_e32 v0, 0xffff8000, v0
	s_waitcnt vmcnt(6)
	s_addc_u32 s31, s21, 0
	v_lshl_add_u32 v0, v13, 11, v0
	v_and_b32_e32 v1, 1, v11
	s_add_u32 s34, s20, 0xdc00
	v_lshl_or_b32 v0, v1, 6, v0
	v_bitop3_b32 v237, s1, v15, v12 bitop3:0xf6
	s_addc_u32 s35, s21, 0
	v_mov_b32_e32 v187, v169
	v_lshl_add_u32 v188, v14, 1, v0
	v_mov_b32_e32 v189, v169
	s_mov_b32 s65, 0
	s_mov_b32 s83, 0
	v_add_u32_e32 v238, 0, v16
	s_lshl_b32 s66, s61, 2
	s_barrier
	s_branch .LBB0_877
.LBB0_876:
	s_or_b64 exec, exec, s[0:1]
	s_mov_b32 s83, s82
	s_and_b64 vcc, exec, s[6:7]
	s_mov_b32 s0, s36
	s_mov_b32 s8, s38
	s_mov_b64 s[2:3], s[42:43]
	s_mov_b64 s[10:11], s[40:41]
	s_cbranch_vccnz .LBB0_915
.LBB0_877:
	s_add_i32 s65, s65, 1
	s_mul_i32 s1, s65, s64
	s_mul_hi_u32 s6, s65, s45
	s_add_i32 s6, s6, s1
	s_mul_i32 s1, s65, s45
	s_add_u32 s12, s1, s44
	s_addc_u32 s13, s6, s46
	s_mov_b32 s82, 0
	s_cmp_lt_u32 s12, 0x400
	s_cbranch_scc1 .Lup_nohalf
	s_sub_u32 s84, s12, 0x400
	s_and_b32 s82, s84, 1
	s_lshr_b32 s85, s84, 1
	s_add_u32 s12, s85, 0x400
	s_cmp_lt_u32 s84, 64
	s_cselect_b32 s12, s12, 0x7fffffff
	s_mov_b32 s13, 0
.Lup_nohalf:
	v_cmp_gt_i64_e64 s[6:7], s[12:13], v[176:177]
	s_and_b64 vcc, exec, s[6:7]
	s_cbranch_vccnz .LBB0_879
	s_ashr_i32 s1, s12, 31
	s_lshr_b32 s1, s1, 29
	s_add_i32 s1, s12, s1
	s_ashr_i32 s9, s1, 3
	s_and_b32 s1, s1, -8
	s_sub_i32 s1, s12, s1
	s_cmp_lt_i32 s1, 0
	s_movk_i32 s14, 0x85
	s_cselect_b32 s14, s14, 0x84
	s_mul_i32 s1, s14, s1
	s_add_i32 s1, s1, s9
	s_mul_hi_i32 s9, s1, 0x2e8ba2e9
	s_lshr_b32 s14, s9, 31
	s_ashr_i32 s9, s9, 5
	s_add_i32 s9, s9, s14
	s_lshl_b32 s14, s9, 3
	s_sub_i32 s15, 48, s14
	s_min_i32 s15, s15, 8
	s_abs_i32 s36, s15
	v_cvt_f32_u32_e32 v0, s36
	s_sub_i32 s38, 0, s36
	s_mulk_i32 s9, 0xb0
	s_sub_i32 s1, s1, s9
	v_rcp_iflag_f32_e32 v0, v0
	s_abs_i32 s9, s1
	s_xor_b32 s37, s1, s15
	s_ashr_i32 s37, s37, 31
	v_mul_f32_e32 v0, 0x4f7ffffe, v0
	v_cvt_u32_f32_e32 v0, v0
	s_nop 0
	v_readfirstlane_b32 s39, v0
	s_mul_i32 s38, s38, s39
	s_mul_hi_u32 s38, s39, s38
	s_add_i32 s39, s39, s38
	s_mul_hi_u32 s38, s9, s39
	s_mul_i32 s39, s38, s36
	s_sub_i32 s9, s9, s39
	s_add_i32 s40, s38, 1
	s_sub_i32 s39, s9, s36
	s_cmp_ge_u32 s9, s36
	s_cselect_b32 s38, s40, s38
	s_cselect_b32 s9, s39, s9
	s_add_i32 s39, s38, 1
	s_cmp_ge_u32 s9, s36
	s_cselect_b32 s9, s39, s38
	s_xor_b32 s9, s9, s37
	s_sub_i32 s36, s9, s37
	s_mul_i32 s9, s36, s15
	s_sub_i32 s1, s1, s9
	s_add_i32 s38, s1, s14
.LBB0_879:
	s_ashr_i32 s39, s38, 31
	v_cmp_lt_i64_e32 vcc, s[12:13], v[178:179]
	s_lshl_b64 s[12:13], s[38:39], 19
	s_add_u32 s40, s49, s12
	s_addc_u32 s41, s50, s13
	s_lshl_b32 s84, s82, 18
	s_add_u32 s40, s40, s84
	s_addc_u32 s41, s41, 0
	s_and_b64 s[12:13], vcc, exec
	s_cselect_b32 s1, s41, s11
	s_cselect_b32 s9, s40, s10
	s_ashr_i32 s37, s36, 31
	s_lshl_b64 s[12:13], s[36:37], 19
	s_add_u32 s42, s51, s12
	s_addc_u32 s43, s52, s13
	s_and_b64 s[12:13], vcc, exec
	s_cselect_b32 s14, s43, s3
	s_cselect_b32 s15, s42, s2
	s_add_u32 s10, s10, 0x40080
	s_addc_u32 s11, s11, 0
	s_add_u32 s37, s2, 0x100
	s_addc_u32 s39, s3, 0
	s_mov_b32 s67, -2
	s_cmp_lg_u32 s83, 0
	s_cbranch_scc1 .Lup_half_peel
	s_add_u32 s2, s10, 0xfffc0080
	s_addc_u32 s3, s11, -1
	s_add_i32 s68, 0, 0x10000
	v_add_u32_e32 v108, s68, v237
	ds_read_b128 v[48:51], v108
	ds_read_b128 v[52:55], v108 offset:1024
	ds_read_b128 v[104:107], v108 offset:2048
	ds_read_b128 v[108:111], v108 offset:3072
	s_cmp_eq_u32 s67, 12
	s_cselect_b32 s13, s1, s3
	s_cselect_b32 s12, s9, s2
	s_cselect_b32 s3, s14, s39
	s_cselect_b32 s2, s15, s37
	v_lshl_add_u64 v[198:199], s[10:11], 0, v[186:187]
	s_add_i32 m0, s54, 0xc000
	ds_read_b128 v[112:115], v238
	ds_read_b128 v[116:119], v238 offset:1024
	ds_read_b128 v[120:123], v238 offset:2048
	ds_read_b128 v[156:159], v238 offset:3072
	ds_read_b128 v[160:163], v238 offset:4096
	ds_read_b128 v[164:167], v238 offset:5120
	ds_read_b128 v[190:193], v238 offset:6144
	ds_read_b128 v[194:197], v238 offset:7168
	global_load_lds_dwordx4 v[198:199], off
	v_lshl_add_u64 v[198:199], s[10:11], 0, v[188:189]
	s_add_i32 m0, s54, 0xe000
	s_nop 0
	global_load_lds_dwordx4 v[198:199], off
	s_waitcnt lgkmcnt(8)
	s_barrier
	s_waitcnt lgkmcnt(0)
	s_setprio 1
	s_waitcnt lgkmcnt(0)
	v_mfma_f32_16x16x32_bf16 v[152:155], v[48:51], v[112:115], 0
	v_mfma_f32_16x16x32_bf16 v[68:71], v[104:107], v[112:115], 0
	v_mfma_f32_16x16x32_bf16 v[148:151], v[48:51], v[120:123], 0
	v_mfma_f32_16x16x32_bf16 v[64:67], v[104:107], v[120:123], 0
	v_mfma_f32_16x16x32_bf16 v[136:139], v[48:51], v[160:163], 0
	v_mfma_f32_16x16x32_bf16 v[44:47], v[104:107], v[160:163], 0
	v_mfma_f32_16x16x32_bf16 v[128:131], v[48:51], v[190:193], 0
	v_mfma_f32_16x16x32_bf16 v[40:43], v[104:107], v[190:193], 0
	v_mfma_f32_16x16x32_bf16 v[152:155], v[52:55], v[116:119], v[152:155]
	v_mfma_f32_16x16x32_bf16 v[68:71], v[108:111], v[116:119], v[68:71]
	v_mfma_f32_16x16x32_bf16 v[148:151], v[52:55], v[156:159], v[148:151]
	v_mfma_f32_16x16x32_bf16 v[64:67], v[108:111], v[156:159], v[64:67]
	v_mfma_f32_16x16x32_bf16 v[136:139], v[52:55], v[164:167], v[136:139]
	v_mfma_f32_16x16x32_bf16 v[44:47], v[108:111], v[164:167], v[44:47]
	v_mfma_f32_16x16x32_bf16 v[128:131], v[52:55], v[194:197], v[128:131]
	v_mfma_f32_16x16x32_bf16 v[40:43], v[108:111], v[194:197], v[40:43]
	s_setprio 0
	s_barrier
	s_add_i32 s70, 0, 0x14000
	s_add_i32 s68, s68, s53
	v_add_u32_e32 v210, s70, v237
	v_lshl_add_u64 v[218:219], s[2:3], 0, v[168:169]
	s_mov_b32 m0, s68
	ds_read_b128 v[198:201], v210
	ds_read_b128 v[202:205], v210 offset:1024
	ds_read_b128 v[206:209], v210 offset:2048
	ds_read_b128 v[210:213], v210 offset:3072
	global_load_lds_dwordx4 v[218:219], off
	v_lshl_add_u64 v[220:221], s[2:3], 0, v[184:185]
	s_add_i32 m0, s68, 0x2000
	s_nop 0
	global_load_lds_dwordx4 v[220:221], off
	s_barrier
	s_waitcnt lgkmcnt(0)
	s_setprio 1
	s_waitcnt lgkmcnt(0)
	v_mfma_f32_16x16x32_bf16 v[144:147], v[198:201], v[112:115], 0
	v_mfma_f32_16x16x32_bf16 v[60:63], v[206:209], v[112:115], 0
	v_mfma_f32_16x16x32_bf16 v[56:59], v[206:209], v[120:123], 0
	v_mfma_f32_16x16x32_bf16 v[36:39], v[206:209], v[160:163], 0
	v_mfma_f32_16x16x32_bf16 v[32:35], v[206:209], v[190:193], 0
	v_mfma_f32_16x16x32_bf16 v[144:147], v[202:205], v[116:119], v[144:147]
	v_mfma_f32_16x16x32_bf16 v[60:63], v[210:213], v[116:119], v[60:63]
	v_mfma_f32_16x16x32_bf16 v[112:115], v[198:201], v[120:123], 0
	v_mfma_f32_16x16x32_bf16 v[56:59], v[210:213], v[156:159], v[56:59]
	v_mfma_f32_16x16x32_bf16 v[116:119], v[198:201], v[160:163], 0
	v_mfma_f32_16x16x32_bf16 v[36:39], v[210:213], v[164:167], v[36:39]
	v_mfma_f32_16x16x32_bf16 v[120:123], v[198:201], v[190:193], 0
	v_mfma_f32_16x16x32_bf16 v[32:35], v[210:213], v[194:197], v[32:35]
	v_mfma_f32_16x16x32_bf16 v[112:115], v[202:205], v[156:159], v[112:115]
	v_mfma_f32_16x16x32_bf16 v[116:119], v[202:205], v[164:167], v[116:119]
	v_mfma_f32_16x16x32_bf16 v[120:123], v[202:205], v[194:197], v[120:123]
	s_setprio 0
	s_mov_b32 m0, s54
	v_lshl_add_u64 v[222:223], s[12:13], 0, v[180:181]
	s_barrier
	ds_read_b128 v[124:127], v238 offset:16384
	ds_read_b128 v[132:135], v238 offset:17408
	ds_read_b128 v[140:143], v238 offset:18432
	ds_read_b128 v[156:159], v238 offset:19456
	ds_read_b128 v[160:163], v238 offset:20480
	ds_read_b128 v[164:167], v238 offset:21504
	ds_read_b128 v[190:193], v238 offset:22528
	ds_read_b128 v[194:197], v238 offset:23552
	global_load_lds_dwordx4 v[222:223], off
	v_lshl_add_u64 v[240:241], s[12:13], 0, v[182:183]
	s_mov_b32 m0, s55
	s_nop 0
	global_load_lds_dwordx4 v[240:241], off
	s_barrier
	s_waitcnt lgkmcnt(0)
	s_setprio 1
	s_waitcnt lgkmcnt(0)
	v_mfma_f32_16x16x32_bf16 v[100:103], v[48:51], v[124:127], 0
	v_mfma_f32_16x16x32_bf16 v[28:31], v[104:107], v[124:127], 0
	v_mfma_f32_16x16x32_bf16 v[96:99], v[48:51], v[140:143], 0
	v_mfma_f32_16x16x32_bf16 v[24:27], v[104:107], v[140:143], 0
	v_mfma_f32_16x16x32_bf16 v[84:87], v[48:51], v[160:163], 0
	v_mfma_f32_16x16x32_bf16 v[12:15], v[104:107], v[160:163], 0
	v_mfma_f32_16x16x32_bf16 v[8:11], v[104:107], v[190:193], 0
	v_mfma_f32_16x16x32_bf16 v[100:103], v[52:55], v[132:135], v[100:103]
	v_mfma_f32_16x16x32_bf16 v[28:31], v[108:111], v[132:135], v[28:31]
	v_mfma_f32_16x16x32_bf16 v[96:99], v[52:55], v[156:159], v[96:99]
	v_mfma_f32_16x16x32_bf16 v[24:27], v[108:111], v[156:159], v[24:27]
	v_mfma_f32_16x16x32_bf16 v[84:87], v[52:55], v[164:167], v[84:87]
	v_mfma_f32_16x16x32_bf16 v[12:15], v[108:111], v[164:167], v[12:15]
	v_mfma_f32_16x16x32_bf16 v[48:51], v[48:51], v[190:193], 0
	v_mfma_f32_16x16x32_bf16 v[8:11], v[108:111], v[194:197], v[8:11]
	v_mfma_f32_16x16x32_bf16 v[48:51], v[52:55], v[194:197], v[48:51]
	s_setprio 0
	s_barrier
	s_add_u32 s68, s2, 0x40000
	s_addc_u32 s69, s3, 0
	s_add_i32 s70, s70, s53
	v_lshl_add_u64 v[52:53], s[68:69], 0, v[168:169]
	s_mov_b32 m0, s70
	s_nop 0
	global_load_lds_dwordx4 v[52:53], off
	v_lshl_add_u64 v[52:53], s[68:69], 0, v[184:185]
	s_add_i32 m0, s70, 0x2000
	s_nop 0
	global_load_lds_dwordx4 v[52:53], off
	s_waitcnt vmcnt(6)
	s_barrier
	s_setprio 1
	v_mfma_f32_16x16x32_bf16 v[76:79], v[198:201], v[140:143], 0
	v_mfma_f32_16x16x32_bf16 v[20:23], v[206:209], v[124:127], 0
	v_mfma_f32_16x16x32_bf16 v[88:91], v[202:205], v[156:159], v[76:79]
	v_mfma_f32_16x16x32_bf16 v[16:19], v[206:209], v[140:143], 0
	v_mfma_f32_16x16x32_bf16 v[76:79], v[198:201], v[160:163], 0
	v_mfma_f32_16x16x32_bf16 v[4:7], v[206:209], v[160:163], 0
	v_mfma_f32_16x16x32_bf16 v[72:75], v[198:201], v[190:193], 0
	v_mfma_f32_16x16x32_bf16 v[0:3], v[206:209], v[190:193], 0
	v_mfma_f32_16x16x32_bf16 v[52:55], v[198:201], v[124:127], 0
	v_mfma_f32_16x16x32_bf16 v[20:23], v[210:213], v[132:135], v[20:23]
	v_mfma_f32_16x16x32_bf16 v[16:19], v[210:213], v[156:159], v[16:19]
	v_mfma_f32_16x16x32_bf16 v[80:83], v[202:205], v[164:167], v[76:79]
	v_mfma_f32_16x16x32_bf16 v[4:7], v[210:213], v[164:167], v[4:7]
	v_mfma_f32_16x16x32_bf16 v[72:75], v[202:205], v[194:197], v[72:75]
	v_mfma_f32_16x16x32_bf16 v[0:3], v[210:213], v[194:197], v[0:3]
	v_mfma_f32_16x16x32_bf16 v[52:55], v[202:205], v[132:135], v[52:55]
	s_setprio 0
	s_add_i32 s68, 0, 0x18000
	v_add_u32_e32 v108, s68, v237
	s_barrier
	ds_read_b128 v[76:79], v108
	ds_read_b128 v[92:95], v108 offset:1024
	ds_read_b128 v[104:107], v108 offset:2048
	ds_read_b128 v[108:111], v108 offset:3072
	s_add_u32 s12, s12, 0x40000
	s_addc_u32 s13, s13, 0
	s_mov_b32 m0, s56
	v_lshl_add_u64 v[140:141], s[12:13], 0, v[180:181]
	ds_read_b128 v[124:127], v238 offset:32768
	ds_read_b128 v[132:135], v238 offset:33792
	ds_read_b128 v[156:159], v238 offset:34816
	ds_read_b128 v[160:163], v238 offset:35840
	ds_read_b128 v[164:167], v238 offset:36864
	ds_read_b128 v[190:193], v238 offset:37888
	ds_read_b128 v[194:197], v238 offset:38912
	ds_read_b128 v[198:201], v238 offset:39936
	global_load_lds_dwordx4 v[140:141], off
	v_lshl_add_u64 v[140:141], s[12:13], 0, v[182:183]
	s_mov_b32 m0, s57
	s_nop 0
	global_load_lds_dwordx4 v[140:141], off
	s_waitcnt lgkmcnt(8)
	s_barrier
	s_waitcnt lgkmcnt(0)
	s_setprio 1
	s_waitcnt lgkmcnt(0)
	v_mfma_f32_16x16x32_bf16 v[140:143], v[76:79], v[124:127], v[152:155]
	v_mfma_f32_16x16x32_bf16 v[152:155], v[92:95], v[132:135], v[140:143]
	v_mfma_f32_16x16x32_bf16 v[68:71], v[104:107], v[124:127], v[68:71]
	v_mfma_f32_16x16x32_bf16 v[140:143], v[76:79], v[156:159], v[148:151]
	v_mfma_f32_16x16x32_bf16 v[64:67], v[104:107], v[156:159], v[64:67]
	v_mfma_f32_16x16x32_bf16 v[136:139], v[76:79], v[164:167], v[136:139]
	v_mfma_f32_16x16x32_bf16 v[44:47], v[104:107], v[164:167], v[44:47]
	v_mfma_f32_16x16x32_bf16 v[128:131], v[76:79], v[194:197], v[128:131]
	v_mfma_f32_16x16x32_bf16 v[40:43], v[104:107], v[194:197], v[40:43]
	v_mfma_f32_16x16x32_bf16 v[68:71], v[108:111], v[132:135], v[68:71]
	v_mfma_f32_16x16x32_bf16 v[148:151], v[92:95], v[160:163], v[140:143]
	v_mfma_f32_16x16x32_bf16 v[64:67], v[108:111], v[160:163], v[64:67]
	v_mfma_f32_16x16x32_bf16 v[136:139], v[92:95], v[190:193], v[136:139]
	v_mfma_f32_16x16x32_bf16 v[44:47], v[108:111], v[190:193], v[44:47]
	v_mfma_f32_16x16x32_bf16 v[128:131], v[92:95], v[198:201], v[128:131]
	v_mfma_f32_16x16x32_bf16 v[40:43], v[108:111], v[198:201], v[40:43]
	s_setprio 0
	s_barrier
	s_add_i32 s12, 0, 0x1c000
	v_add_u32_e32 v140, s12, v237
	s_add_i32 s13, s68, s53
	ds_read_b128 v[202:205], v140
	ds_read_b128 v[206:209], v140 offset:1024
	ds_read_b128 v[210:213], v140 offset:2048
	ds_read_b128 v[214:217], v140 offset:3072
	v_lshl_add_u64 v[140:141], v[218:219], 0, s[78:79]
	s_mov_b32 m0, s13
	s_nop 0
	global_load_lds_dwordx4 v[140:141], off
	v_lshl_add_u64 v[140:141], v[220:221], 0, s[78:79]
	s_add_i32 m0, s13, 0x2000
	s_nop 0
	global_load_lds_dwordx4 v[140:141], off
	s_barrier
	s_waitcnt lgkmcnt(0)
	s_setprio 1
	s_waitcnt lgkmcnt(0)
	v_mfma_f32_16x16x32_bf16 v[140:143], v[202:205], v[124:127], v[144:147]
	v_mfma_f32_16x16x32_bf16 v[112:115], v[202:205], v[156:159], v[112:115]
	v_mfma_f32_16x16x32_bf16 v[144:147], v[206:209], v[132:135], v[140:143]
	v_mfma_f32_16x16x32_bf16 v[60:63], v[210:213], v[124:127], v[60:63]
	v_mfma_f32_16x16x32_bf16 v[140:143], v[206:209], v[160:163], v[112:115]
	v_mfma_f32_16x16x32_bf16 v[112:115], v[202:205], v[164:167], v[116:119]
	v_mfma_f32_16x16x32_bf16 v[60:63], v[214:217], v[132:135], v[60:63]
	v_mfma_f32_16x16x32_bf16 v[56:59], v[210:213], v[156:159], v[56:59]
	v_mfma_f32_16x16x32_bf16 v[132:135], v[206:209], v[190:193], v[112:115]
	v_mfma_f32_16x16x32_bf16 v[36:39], v[210:213], v[164:167], v[36:39]
	v_mfma_f32_16x16x32_bf16 v[112:115], v[202:205], v[194:197], v[120:123]
	v_mfma_f32_16x16x32_bf16 v[32:35], v[210:213], v[194:197], v[32:35]
	v_mfma_f32_16x16x32_bf16 v[56:59], v[214:217], v[160:163], v[56:59]
	v_mfma_f32_16x16x32_bf16 v[36:39], v[214:217], v[190:193], v[36:39]
	v_mfma_f32_16x16x32_bf16 v[124:127], v[206:209], v[198:201], v[112:115]
	v_mfma_f32_16x16x32_bf16 v[32:35], v[214:217], v[198:201], v[32:35]
	s_setprio 0
	s_mov_b32 m0, s62
	v_lshl_add_u64 v[198:199], v[222:223], 0, s[78:79]
	s_barrier
	ds_read_b128 v[112:115], v238 offset:49152
	ds_read_b128 v[116:119], v238 offset:50176
	ds_read_b128 v[120:123], v238 offset:51200
	ds_read_b128 v[156:159], v238 offset:52224
	ds_read_b128 v[160:163], v238 offset:53248
	ds_read_b128 v[164:167], v238 offset:54272
	ds_read_b128 v[190:193], v238 offset:55296
	ds_read_b128 v[194:197], v238 offset:56320
	global_load_lds_dwordx4 v[198:199], off
	v_lshl_add_u64 v[198:199], v[240:241], 0, s[78:79]
	s_mov_b32 m0, s63
	s_nop 0
	global_load_lds_dwordx4 v[198:199], off
	s_barrier
	s_waitcnt lgkmcnt(0)
	s_setprio 1
	s_waitcnt lgkmcnt(0)
	v_mfma_f32_16x16x32_bf16 v[100:103], v[76:79], v[112:115], v[100:103]
	v_mfma_f32_16x16x32_bf16 v[28:31], v[104:107], v[112:115], v[28:31]
	v_mfma_f32_16x16x32_bf16 v[96:99], v[76:79], v[120:123], v[96:99]
	v_mfma_f32_16x16x32_bf16 v[24:27], v[104:107], v[120:123], v[24:27]
	v_mfma_f32_16x16x32_bf16 v[84:87], v[76:79], v[160:163], v[84:87]
	v_mfma_f32_16x16x32_bf16 v[12:15], v[104:107], v[160:163], v[12:15]
	v_mfma_f32_16x16x32_bf16 v[48:51], v[76:79], v[190:193], v[48:51]
	v_mfma_f32_16x16x32_bf16 v[8:11], v[104:107], v[190:193], v[8:11]
	v_mfma_f32_16x16x32_bf16 v[100:103], v[92:95], v[116:119], v[100:103]
	v_mfma_f32_16x16x32_bf16 v[28:31], v[108:111], v[116:119], v[28:31]
	v_mfma_f32_16x16x32_bf16 v[96:99], v[92:95], v[156:159], v[96:99]
	v_mfma_f32_16x16x32_bf16 v[24:27], v[108:111], v[156:159], v[24:27]
	v_mfma_f32_16x16x32_bf16 v[84:87], v[92:95], v[164:167], v[84:87]
	v_mfma_f32_16x16x32_bf16 v[12:15], v[108:111], v[164:167], v[12:15]
	v_mfma_f32_16x16x32_bf16 v[76:79], v[92:95], v[194:197], v[48:51]
	v_mfma_f32_16x16x32_bf16 v[8:11], v[108:111], v[194:197], v[8:11]
	s_setprio 0
	s_barrier
	s_add_u32 s2, s2, 0x40080
	s_addc_u32 s3, s3, 0
	s_add_i32 s12, s12, s53
	v_lshl_add_u64 v[48:49], s[2:3], 0, v[168:169]
	s_mov_b32 m0, s12
	s_nop 0
	global_load_lds_dwordx4 v[48:49], off
	v_lshl_add_u64 v[48:49], s[2:3], 0, v[184:185]
	s_add_i32 m0, s12, 0x2000
	s_nop 0
	global_load_lds_dwordx4 v[48:49], off
	s_waitcnt vmcnt(6)
	s_barrier
	s_setprio 1
	v_mfma_f32_16x16x32_bf16 v[48:51], v[202:205], v[112:115], v[52:55]
	v_mfma_f32_16x16x32_bf16 v[92:95], v[206:209], v[116:119], v[48:51]
	v_mfma_f32_16x16x32_bf16 v[48:51], v[202:205], v[120:123], v[88:91]
	v_mfma_f32_16x16x32_bf16 v[88:91], v[206:209], v[156:159], v[48:51]
	v_mfma_f32_16x16x32_bf16 v[48:51], v[202:205], v[160:163], v[80:83]
	v_mfma_f32_16x16x32_bf16 v[20:23], v[210:213], v[112:115], v[20:23]
	v_mfma_f32_16x16x32_bf16 v[16:19], v[210:213], v[120:123], v[16:19]
	v_mfma_f32_16x16x32_bf16 v[80:83], v[206:209], v[164:167], v[48:51]
	v_mfma_f32_16x16x32_bf16 v[4:7], v[210:213], v[160:163], v[4:7]
	v_mfma_f32_16x16x32_bf16 v[48:51], v[202:205], v[190:193], v[72:75]
	v_mfma_f32_16x16x32_bf16 v[0:3], v[210:213], v[190:193], v[0:3]
	v_mfma_f32_16x16x32_bf16 v[20:23], v[214:217], v[116:119], v[20:23]
	v_mfma_f32_16x16x32_bf16 v[16:19], v[214:217], v[156:159], v[16:19]
	v_mfma_f32_16x16x32_bf16 v[4:7], v[214:217], v[164:167], v[4:7]
	v_mfma_f32_16x16x32_bf16 v[72:75], v[206:209], v[194:197], v[48:51]
	v_mfma_f32_16x16x32_bf16 v[0:3], v[214:217], v[194:197], v[0:3]
	s_setprio 0
	s_add_i32 s67, s67, 2
	s_add_u32 s10, s10, 0x100
	s_addc_u32 s11, s11, 0
	s_add_u32 s37, s37, 0x100
	s_addc_u32 s39, s39, 0
	s_cmp_gt_u32 s67, 13
	s_barrier

.Lup_epi:
	v_mov_b32_e32 v239, v235
	v_mov_b32_e32 v48, v236
	s_cmp_lt_i32 s8, 16
	s_mov_b64 s[2:3], 0
	s_cbranch_scc1 .LBB0_883
	s_add_i32 s1, s8, -16
	s_lshr_b32 s1, s1, 3
	s_add_i32 s1, s1, 1
	s_mul_hi_u32 s3, s1, 0x1600
	s_mul_i32 s2, s1, 0x1600
.LBB0_883:
	s_lshl_b64 s[2:3], s[2:3], 2
	s_add_u32 s1, s58, s2
	s_addc_u32 s9, s59, s3
	s_lshl_b32 s2, s0, 8
	s_ashr_i32 s3, s2, 31
	s_lshl_b64 s[2:3], s[2:3], 2
	s_add_u32 s1, s1, s2
	s_addc_u32 s3, s9, s3
	s_add_u32 s2, s1, s66
	s_addc_u32 s3, s3, 0
	s_lshl_b32 s1, s8, 8
	s_add_i32 s1, s1, s60
	s_lshl_b32 s84, s83, 7
	s_add_i32 s1, s1, s84
	v_add_u32_e32 v192, s1, v239
	v_ashrrev_i32_e32 v193, 31, v192
	v_lshl_add_u64 v[104:105], v[192:193], 2, s[22:23]
	global_load_dword v193, v[104:105], off
	global_load_dword v196, v[104:105], off offset:64
	s_lshl_b32 s0, s0, 7
	v_lshlrev_b32_e32 v106, 3, v48
	s_or_b32 s0, s0, s61
	v_add_u32_e32 v190, s0, v106
	v_ashrrev_i32_e32 v107, 31, v106
	v_ashrrev_i32_e32 v191, 31, v190
	v_lshl_add_u64 v[48:49], v[106:107], 2, s[2:3]
	v_lshlrev_b64 v[106:107], 2, v[190:191]
	global_load_dwordx4 v[120:123], v[48:49], off
	global_load_dwordx4 v[116:119], v[48:49], off offset:512
	global_load_dwordx4 v[52:55], v[48:49], off offset:16
	s_nop 0
	global_load_dwordx4 v[48:51], v[48:49], off offset:528
	s_nop 0
	global_load_dword v243, v[104:105], off offset:128
	global_load_dword v242, v[104:105], off offset:192
	global_load_dword v241, v[104:105], off offset:512
	global_load_dword v240, v[104:105], off offset:576
	global_load_dword v199, v[104:105], off offset:640
	global_load_dword v197, v[104:105], off offset:704
	v_lshl_add_u64 v[194:195], s[20:21], 0, v[106:107]
	v_lshl_add_u64 v[104:105], s[24:25], 0, v[106:107]
	v_lshl_add_u64 v[108:109], s[26:27], 0, v[106:107]
	v_lshl_add_u64 v[110:111], s[28:29], 0, v[106:107]
	v_lshl_add_u64 v[160:161], s[30:31], 0, v[106:107]
	v_lshl_add_u64 v[200:201], s[34:35], 0, v[106:107]
	global_load_dwordx4 v[220:223], v[194:195], off offset:16
	global_load_dwordx4 v[156:159], v[194:195], off
	s_nop 0
	global_load_dwordx4 v[204:207], v[104:105], off offset:16
	global_load_dwordx4 v[104:107], v[104:105], off
	s_nop 0
	global_load_dwordx4 v[208:211], v[108:109], off offset:16
	global_load_dwordx4 v[164:167], v[108:109], off
	global_load_dwordx4 v[212:215], v[110:111], off offset:16
	global_load_dwordx4 v[112:115], v[110:111], off
	s_nop 0
	global_load_dwordx4 v[216:219], v[160:161], off offset:16
	global_load_dwordx4 v[160:163], v[160:161], off
	s_nop 0
	global_load_dwordx4 v[108:111], v[200:201], off
	global_load_dwordx4 v[200:203], v[200:201], off offset:16
	v_cmp_ne_u32_e64 s[10:11], 0, v239
	v_cmp_ne_u32_e64 s[8:9], 15, v239
	v_cmp_gt_u32_e64 s[12:13], 2, v239
	v_cmp_lt_u32_e64 s[14:15], 13, v239
	s_mov_b32 s0, 0xbfb8aa3b
	s_mov_b32 s1, 0xbfb8aa3b
	s_mov_b64 s[2:3], 0x16000
	s_waitcnt vmcnt(0)
	v_fmamk_f32 v244, v193, 0x3a800000, v225
	v_fmamk_f32 v196, v196, 0x3a800000, v225
	v_fmamk_f32 v246, v243, 0x3a800000, v225
	v_fmamk_f32 v242, v242, 0x3a800000, v225
	v_fmamk_f32 v248, v241, 0x3a800000, v225
	v_fmamk_f32 v240, v240, 0x3a800000, v225
	v_fmamk_f32 v198, v199, 0x3a800000, v225
	v_fmamk_f32 v250, v197, 0x3a800000, v225
	v_rsq_f32_e32 v244, v244
	v_rsq_f32_e32 v196, v196
	v_rsq_f32_e32 v246, v246
	v_rsq_f32_e32 v242, v242
	v_rsq_f32_e32 v248, v248
	v_rsq_f32_e32 v240, v240
	v_rsq_f32_e32 v198, v198
	v_rsq_f32_e32 v250, v250
	v_pk_fma_f32 v[152:153], v[152:153], v[244:245], v[120:121] op_sel_hi:[1,0,1]
	v_pk_fma_f32 v[154:155], v[154:155], v[244:245], v[122:123] op_sel_hi:[1,0,1]
	v_pk_fma_f32 v[68:69], v[68:69], v[244:245], v[52:53] op_sel_hi:[1,0,1]
	v_pk_fma_f32 v[70:71], v[70:71], v[244:245], v[54:55] op_sel_hi:[1,0,1]
	v_pk_fma_f32 v[144:145], v[144:145], v[244:245], v[116:117] op_sel_hi:[1,0,1]
	v_pk_fma_f32 v[146:147], v[146:147], v[244:245], v[118:119] op_sel_hi:[1,0,1]
	v_pk_fma_f32 v[60:61], v[60:61], v[244:245], v[48:49] op_sel_hi:[1,0,1]
	v_pk_fma_f32 v[62:63], v[62:63], v[244:245], v[50:51] op_sel_hi:[1,0,1]
	v_pk_fma_f32 v[148:149], v[148:149], v[196:197], v[120:121] op_sel_hi:[1,0,1]
	v_pk_fma_f32 v[150:151], v[150:151], v[196:197], v[122:123] op_sel_hi:[1,0,1]
	v_pk_fma_f32 v[64:65], v[64:65], v[196:197], v[52:53] op_sel_hi:[1,0,1]
	v_pk_fma_f32 v[66:67], v[66:67], v[196:197], v[54:55] op_sel_hi:[1,0,1]
	v_pk_fma_f32 v[140:141], v[140:141], v[196:197], v[116:117] op_sel_hi:[1,0,1]
	v_pk_fma_f32 v[142:143], v[142:143], v[196:197], v[118:119] op_sel_hi:[1,0,1]
	v_pk_fma_f32 v[56:57], v[56:57], v[196:197], v[48:49] op_sel_hi:[1,0,1]
	v_pk_fma_f32 v[58:59], v[58:59], v[196:197], v[50:51] op_sel_hi:[1,0,1]
	v_pk_fma_f32 v[136:137], v[136:137], v[246:247], v[120:121] op_sel_hi:[1,0,1]
	v_pk_fma_f32 v[138:139], v[138:139], v[246:247], v[122:123] op_sel_hi:[1,0,1]
	v_pk_fma_f32 v[44:45], v[44:45], v[246:247], v[52:53] op_sel_hi:[1,0,1]
	v_pk_fma_f32 v[46:47], v[46:47], v[246:247], v[54:55] op_sel_hi:[1,0,1]
	v_pk_fma_f32 v[132:133], v[132:133], v[246:247], v[116:117] op_sel_hi:[1,0,1]
	v_pk_fma_f32 v[134:135], v[134:135], v[246:247], v[118:119] op_sel_hi:[1,0,1]
	v_pk_fma_f32 v[36:37], v[36:37], v[246:247], v[48:49] op_sel_hi:[1,0,1]
	v_pk_fma_f32 v[38:39], v[38:39], v[246:247], v[50:51] op_sel_hi:[1,0,1]
	v_pk_fma_f32 v[128:129], v[128:129], v[242:243], v[120:121] op_sel_hi:[1,0,1]
	v_pk_fma_f32 v[130:131], v[130:131], v[242:243], v[122:123] op_sel_hi:[1,0,1]
	v_pk_fma_f32 v[40:41], v[40:41], v[242:243], v[52:53] op_sel_hi:[1,0,1]
	v_pk_fma_f32 v[42:43], v[42:43], v[242:243], v[54:55] op_sel_hi:[1,0,1]
	v_pk_fma_f32 v[124:125], v[124:125], v[242:243], v[116:117] op_sel_hi:[1,0,1]
	v_pk_fma_f32 v[126:127], v[126:127], v[242:243], v[118:119] op_sel_hi:[1,0,1]
	v_pk_fma_f32 v[32:33], v[32:33], v[242:243], v[48:49] op_sel_hi:[1,0,1]
	v_pk_fma_f32 v[34:35], v[34:35], v[242:243], v[50:51] op_sel_hi:[1,0,1]
	v_pk_fma_f32 v[100:101], v[100:101], v[248:249], v[120:121] op_sel_hi:[1,0,1]
	v_pk_fma_f32 v[102:103], v[102:103], v[248:249], v[122:123] op_sel_hi:[1,0,1]
	v_pk_fma_f32 v[28:29], v[28:29], v[248:249], v[52:53] op_sel_hi:[1,0,1]
	v_pk_fma_f32 v[30:31], v[30:31], v[248:249], v[54:55] op_sel_hi:[1,0,1]
	v_pk_fma_f32 v[92:93], v[92:93], v[248:249], v[116:117] op_sel_hi:[1,0,1]
	v_pk_fma_f32 v[94:95], v[94:95], v[248:249], v[118:119] op_sel_hi:[1,0,1]
	v_pk_fma_f32 v[20:21], v[20:21], v[248:249], v[48:49] op_sel_hi:[1,0,1]
	v_pk_fma_f32 v[22:23], v[22:23], v[248:249], v[50:51] op_sel_hi:[1,0,1]
	v_pk_fma_f32 v[96:97], v[96:97], v[240:241], v[120:121] op_sel_hi:[1,0,1]
	v_pk_fma_f32 v[98:99], v[98:99], v[240:241], v[122:123] op_sel_hi:[1,0,1]
	v_pk_fma_f32 v[24:25], v[24:25], v[240:241], v[52:53] op_sel_hi:[1,0,1]
	v_pk_fma_f32 v[26:27], v[26:27], v[240:241], v[54:55] op_sel_hi:[1,0,1]
	v_pk_fma_f32 v[88:89], v[88:89], v[240:241], v[116:117] op_sel_hi:[1,0,1]
	v_pk_fma_f32 v[90:91], v[90:91], v[240:241], v[118:119] op_sel_hi:[1,0,1]
	v_pk_fma_f32 v[16:17], v[16:17], v[240:241], v[48:49] op_sel_hi:[1,0,1]
	v_pk_fma_f32 v[18:19], v[18:19], v[240:241], v[50:51] op_sel_hi:[1,0,1]
	v_pk_fma_f32 v[84:85], v[84:85], v[198:199], v[120:121] op_sel_hi:[1,0,1]
	v_pk_fma_f32 v[86:87], v[86:87], v[198:199], v[122:123] op_sel_hi:[1,0,1]
	v_pk_fma_f32 v[12:13], v[12:13], v[198:199], v[52:53] op_sel_hi:[1,0,1]
	v_pk_fma_f32 v[14:15], v[14:15], v[198:199], v[54:55] op_sel_hi:[1,0,1]
	v_pk_fma_f32 v[80:81], v[80:81], v[198:199], v[116:117] op_sel_hi:[1,0,1]
	v_pk_fma_f32 v[82:83], v[82:83], v[198:199], v[118:119] op_sel_hi:[1,0,1]
	v_pk_fma_f32 v[4:5], v[4:5], v[198:199], v[48:49] op_sel_hi:[1,0,1]
	v_pk_fma_f32 v[6:7], v[6:7], v[198:199], v[50:51] op_sel_hi:[1,0,1]
	v_pk_fma_f32 v[76:77], v[76:77], v[250:251], v[120:121] op_sel_hi:[1,0,1]
	v_pk_fma_f32 v[78:79], v[78:79], v[250:251], v[122:123] op_sel_hi:[1,0,1]
	v_pk_fma_f32 v[8:9], v[8:9], v[250:251], v[52:53] op_sel_hi:[1,0,1]
	v_pk_fma_f32 v[10:11], v[10:11], v[250:251], v[54:55] op_sel_hi:[1,0,1]
	v_pk_fma_f32 v[72:73], v[72:73], v[250:251], v[116:117] op_sel_hi:[1,0,1]
	v_pk_fma_f32 v[74:75], v[74:75], v[250:251], v[118:119] op_sel_hi:[1,0,1]
	v_pk_fma_f32 v[0:1], v[0:1], v[250:251], v[48:49] op_sel_hi:[1,0,1]
	v_pk_fma_f32 v[2:3], v[2:3], v[250:251], v[50:51] op_sel_hi:[1,0,1]
	v_mov_b64_e32 v[246:247], s[16:17]
	v_mad_i64_i32 v[246:247], vcc, v192, s90, v[246:247]
	v_lshl_add_u64 v[246:247], v[190:191], 1, v[246:247]
	v_ashrrev_i32_e32 v194, 4, v192
	v_and_b32_e32 v194, -4, v194
	v_add_u32_e32 v194, v194, v239
	v_mov_b64_e32 v[248:249], s[18:19]
	v_mad_i64_i32 v[248:249], vcc, v194, s91, v[248:249]
	v_lshl_add_u64 v[248:249], v[190:191], 1, v[248:249]
	v_mov_b32_e32 v244, v246
	v_mov_b32_e32 v245, v247
	v_mov_b32_e32 v250, v248
	v_mov_b32_e32 v251, v249
	v_add_co_u32_e32 v194, vcc, 0x1000, v250
	s_nop 1
	v_addc_co_u32_e32 v195, vcc, 0, v251, vcc
	v_mul_f32_e32 v116, v164, v152
	v_mul_f32_e32 v117, v165, v153
	v_mul_f32_e32 v118, v166, v154
	v_mul_f32_e32 v119, v167, v155
	v_mul_f32_e32 v120, v112, v144
	v_mul_f32_e32 v121, v113, v145
	v_mul_f32_e32 v122, v114, v146
	v_mul_f32_e32 v123, v115, v147
	v_fmac_f32_dpp v116, v152, v156 row_shr:1 row_mask:0xf bank_mask:0xf bound_ctrl:1
	v_fmac_f32_dpp v117, v153, v157 row_shr:1 row_mask:0xf bank_mask:0xf bound_ctrl:1
	v_fmac_f32_dpp v118, v154, v158 row_shr:1 row_mask:0xf bank_mask:0xf bound_ctrl:1
	v_fmac_f32_dpp v119, v155, v159 row_shr:1 row_mask:0xf bank_mask:0xf bound_ctrl:1
	v_fmac_f32_dpp v120, v144, v104 row_shr:1 row_mask:0xf bank_mask:0xf bound_ctrl:1
	v_fmac_f32_dpp v121, v145, v105 row_shr:1 row_mask:0xf bank_mask:0xf bound_ctrl:1
	v_fmac_f32_dpp v122, v146, v106 row_shr:1 row_mask:0xf bank_mask:0xf bound_ctrl:1
	v_fmac_f32_dpp v123, v147, v107 row_shr:1 row_mask:0xf bank_mask:0xf bound_ctrl:1
	v_fmac_f32_dpp v116, v152, v160 row_shl:1 row_mask:0xf bank_mask:0xf bound_ctrl:1
	v_fmac_f32_dpp v117, v153, v161 row_shl:1 row_mask:0xf bank_mask:0xf bound_ctrl:1
	v_fmac_f32_dpp v118, v154, v162 row_shl:1 row_mask:0xf bank_mask:0xf bound_ctrl:1
	v_fmac_f32_dpp v119, v155, v163 row_shl:1 row_mask:0xf bank_mask:0xf bound_ctrl:1
	v_fmac_f32_dpp v120, v144, v108 row_shl:1 row_mask:0xf bank_mask:0xf bound_ctrl:1
	v_fmac_f32_dpp v121, v145, v109 row_shl:1 row_mask:0xf bank_mask:0xf bound_ctrl:1
	v_fmac_f32_dpp v122, v146, v110 row_shl:1 row_mask:0xf bank_mask:0xf bound_ctrl:1
	v_fmac_f32_dpp v123, v147, v111 row_shl:1 row_mask:0xf bank_mask:0xf bound_ctrl:1
	v_fmac_f32_dpp v116, v148, v160 row_shr:15 row_mask:0xf bank_mask:0xf bound_ctrl:1
	v_fmac_f32_dpp v117, v149, v161 row_shr:15 row_mask:0xf bank_mask:0xf bound_ctrl:1
	v_fmac_f32_dpp v118, v150, v162 row_shr:15 row_mask:0xf bank_mask:0xf bound_ctrl:1
	v_fmac_f32_dpp v119, v151, v163 row_shr:15 row_mask:0xf bank_mask:0xf bound_ctrl:1
	v_fmac_f32_dpp v120, v140, v108 row_shr:15 row_mask:0xf bank_mask:0xf bound_ctrl:1
	v_fmac_f32_dpp v121, v141, v109 row_shr:15 row_mask:0xf bank_mask:0xf bound_ctrl:1
	v_fmac_f32_dpp v122, v142, v110 row_shr:15 row_mask:0xf bank_mask:0xf bound_ctrl:1
	v_fmac_f32_dpp v123, v143, v111 row_shr:15 row_mask:0xf bank_mask:0xf bound_ctrl:1
	v_pk_mul_f32 v[48:49], v[116:117], s[0:1]
	v_pk_mul_f32 v[50:51], v[118:119], s[0:1]
	v_pk_mul_f32 v[52:53], v[116:117], v[120:121]
	v_pk_mul_f32 v[54:55], v[118:119], v[122:123]
	v_exp_f32_e32 v48, v48
	v_exp_f32_e32 v49, v49
	v_exp_f32_e32 v50, v50
	v_exp_f32_e32 v51, v51
	v_cvt_pk_bf16_f32 v196, v152, v153
	v_cvt_pk_bf16_f32 v197, v154, v155
	v_cvt_pk_bf16_f32 v198, v144, v145
	v_cvt_pk_bf16_f32 v199, v146, v147
	v_pk_add_f32 v[48:49], v[48:49], 1.0 op_sel_hi:[1,0]
	v_pk_add_f32 v[50:51], v[50:51], 1.0 op_sel_hi:[1,0]
	v_rcp_f32_e32 v48, v48
	v_rcp_f32_e32 v49, v49
	v_rcp_f32_e32 v50, v50
	v_rcp_f32_e32 v51, v51
	s_nop 0
	v_pk_mul_f32 v[52:53], v[52:53], v[48:49]
	v_pk_mul_f32 v[54:55], v[54:55], v[50:51]
	v_cvt_pk_bf16_f32 v252, v52, v53
	v_cvt_pk_bf16_f32 v253, v54, v55
	s_and_saveexec_b64 vcc, s[10:11]
	global_store_dwordx2 v[244:245], v[252:253], off
	s_mov_b64 exec, vcc
	s_and_saveexec_b64 vcc, s[12:13]
	global_store_dwordx2 v[250:251], v[196:197], off
	global_store_dwordx2 v[194:195], v[198:199], off offset:1536
	s_mov_b64 exec, vcc
	v_lshl_add_u64 v[244:245], v[244:245], 0, s[2:3]
	v_mul_f32_e32 v116, v164, v148
	v_mul_f32_e32 v117, v165, v149
	v_mul_f32_e32 v118, v166, v150
	v_mul_f32_e32 v119, v167, v151
	v_mul_f32_e32 v120, v112, v140
	v_mul_f32_e32 v121, v113, v141
	v_mul_f32_e32 v122, v114, v142
	v_mul_f32_e32 v123, v115, v143
	v_fmac_f32_dpp v116, v148, v156 row_shr:1 row_mask:0xf bank_mask:0xf bound_ctrl:1
	v_fmac_f32_dpp v117, v149, v157 row_shr:1 row_mask:0xf bank_mask:0xf bound_ctrl:1
	v_fmac_f32_dpp v118, v150, v158 row_shr:1 row_mask:0xf bank_mask:0xf bound_ctrl:1
	v_fmac_f32_dpp v119, v151, v159 row_shr:1 row_mask:0xf bank_mask:0xf bound_ctrl:1
	v_fmac_f32_dpp v120, v140, v104 row_shr:1 row_mask:0xf bank_mask:0xf bound_ctrl:1
	v_fmac_f32_dpp v121, v141, v105 row_shr:1 row_mask:0xf bank_mask:0xf bound_ctrl:1
	v_fmac_f32_dpp v122, v142, v106 row_shr:1 row_mask:0xf bank_mask:0xf bound_ctrl:1
	v_fmac_f32_dpp v123, v143, v107 row_shr:1 row_mask:0xf bank_mask:0xf bound_ctrl:1
	v_fmac_f32_dpp v116, v148, v160 row_shl:1 row_mask:0xf bank_mask:0xf bound_ctrl:1
	v_fmac_f32_dpp v117, v149, v161 row_shl:1 row_mask:0xf bank_mask:0xf bound_ctrl:1
	v_fmac_f32_dpp v118, v150, v162 row_shl:1 row_mask:0xf bank_mask:0xf bound_ctrl:1
	v_fmac_f32_dpp v119, v151, v163 row_shl:1 row_mask:0xf bank_mask:0xf bound_ctrl:1
	v_fmac_f32_dpp v120, v140, v108 row_shl:1 row_mask:0xf bank_mask:0xf bound_ctrl:1
	v_fmac_f32_dpp v121, v141, v109 row_shl:1 row_mask:0xf bank_mask:0xf bound_ctrl:1
	v_fmac_f32_dpp v122, v142, v110 row_shl:1 row_mask:0xf bank_mask:0xf bound_ctrl:1
	v_fmac_f32_dpp v123, v143, v111 row_shl:1 row_mask:0xf bank_mask:0xf bound_ctrl:1
	v_fmac_f32_dpp v116, v152, v156 row_shl:15 row_mask:0xf bank_mask:0xf bound_ctrl:1
	v_fmac_f32_dpp v117, v153, v157 row_shl:15 row_mask:0xf bank_mask:0xf bound_ctrl:1
	v_fmac_f32_dpp v118, v154, v158 row_shl:15 row_mask:0xf bank_mask:0xf bound_ctrl:1
	v_fmac_f32_dpp v119, v155, v159 row_shl:15 row_mask:0xf bank_mask:0xf bound_ctrl:1
	v_fmac_f32_dpp v120, v144, v104 row_shl:15 row_mask:0xf bank_mask:0xf bound_ctrl:1
	v_fmac_f32_dpp v121, v145, v105 row_shl:15 row_mask:0xf bank_mask:0xf bound_ctrl:1
	v_fmac_f32_dpp v122, v146, v106 row_shl:15 row_mask:0xf bank_mask:0xf bound_ctrl:1
	v_fmac_f32_dpp v123, v147, v107 row_shl:15 row_mask:0xf bank_mask:0xf bound_ctrl:1
	v_fmac_f32_dpp v116, v136, v160 row_shr:15 row_mask:0xf bank_mask:0xf bound_ctrl:1
	v_fmac_f32_dpp v117, v137, v161 row_shr:15 row_mask:0xf bank_mask:0xf bound_ctrl:1
	v_fmac_f32_dpp v118, v138, v162 row_shr:15 row_mask:0xf bank_mask:0xf bound_ctrl:1
	v_fmac_f32_dpp v119, v139, v163 row_shr:15 row_mask:0xf bank_mask:0xf bound_ctrl:1
	v_fmac_f32_dpp v120, v132, v108 row_shr:15 row_mask:0xf bank_mask:0xf bound_ctrl:1
	v_fmac_f32_dpp v121, v133, v109 row_shr:15 row_mask:0xf bank_mask:0xf bound_ctrl:1
	v_fmac_f32_dpp v122, v134, v110 row_shr:15 row_mask:0xf bank_mask:0xf bound_ctrl:1
	v_fmac_f32_dpp v123, v135, v111 row_shr:15 row_mask:0xf bank_mask:0xf bound_ctrl:1
	v_pk_mul_f32 v[48:49], v[116:117], s[0:1]
	v_pk_mul_f32 v[50:51], v[118:119], s[0:1]
	v_pk_mul_f32 v[52:53], v[116:117], v[120:121]
	v_pk_mul_f32 v[54:55], v[118:119], v[122:123]
	v_exp_f32_e32 v48, v48
	v_exp_f32_e32 v49, v49
	v_exp_f32_e32 v50, v50
	v_exp_f32_e32 v51, v51
	s_nop 0
	v_pk_add_f32 v[48:49], v[48:49], 1.0 op_sel_hi:[1,0]
	v_pk_add_f32 v[50:51], v[50:51], 1.0 op_sel_hi:[1,0]
	v_rcp_f32_e32 v48, v48
	v_rcp_f32_e32 v49, v49
	v_rcp_f32_e32 v50, v50
	v_rcp_f32_e32 v51, v51
	s_nop 0
	v_pk_mul_f32 v[52:53], v[52:53], v[48:49]
	v_pk_mul_f32 v[54:55], v[54:55], v[50:51]
	v_cvt_pk_bf16_f32 v252, v52, v53
	v_cvt_pk_bf16_f32 v253, v54, v55
	global_store_dwordx2 v[244:245], v[252:253], off
	v_lshl_add_u64 v[244:245], v[244:245], 0, s[2:3]
	v_mul_f32_e32 v116, v164, v136
	v_mul_f32_e32 v117, v165, v137
	v_mul_f32_e32 v118, v166, v138
	v_mul_f32_e32 v119, v167, v139
	v_mul_f32_e32 v120, v112, v132
	v_mul_f32_e32 v121, v113, v133
	v_mul_f32_e32 v122, v114, v134
	v_mul_f32_e32 v123, v115, v135
	v_fmac_f32_dpp v116, v136, v156 row_shr:1 row_mask:0xf bank_mask:0xf bound_ctrl:1
	v_fmac_f32_dpp v117, v137, v157 row_shr:1 row_mask:0xf bank_mask:0xf bound_ctrl:1
	v_fmac_f32_dpp v118, v138, v158 row_shr:1 row_mask:0xf bank_mask:0xf bound_ctrl:1
	v_fmac_f32_dpp v119, v139, v159 row_shr:1 row_mask:0xf bank_mask:0xf bound_ctrl:1
	v_fmac_f32_dpp v120, v132, v104 row_shr:1 row_mask:0xf bank_mask:0xf bound_ctrl:1
	v_fmac_f32_dpp v121, v133, v105 row_shr:1 row_mask:0xf bank_mask:0xf bound_ctrl:1
	v_fmac_f32_dpp v122, v134, v106 row_shr:1 row_mask:0xf bank_mask:0xf bound_ctrl:1
	v_fmac_f32_dpp v123, v135, v107 row_shr:1 row_mask:0xf bank_mask:0xf bound_ctrl:1
	v_fmac_f32_dpp v116, v136, v160 row_shl:1 row_mask:0xf bank_mask:0xf bound_ctrl:1
	v_fmac_f32_dpp v117, v137, v161 row_shl:1 row_mask:0xf bank_mask:0xf bound_ctrl:1
	v_fmac_f32_dpp v118, v138, v162 row_shl:1 row_mask:0xf bank_mask:0xf bound_ctrl:1
	v_fmac_f32_dpp v119, v139, v163 row_shl:1 row_mask:0xf bank_mask:0xf bound_ctrl:1
	v_fmac_f32_dpp v120, v132, v108 row_shl:1 row_mask:0xf bank_mask:0xf bound_ctrl:1
	v_fmac_f32_dpp v121, v133, v109 row_shl:1 row_mask:0xf bank_mask:0xf bound_ctrl:1
	v_fmac_f32_dpp v122, v134, v110 row_shl:1 row_mask:0xf bank_mask:0xf bound_ctrl:1
	v_fmac_f32_dpp v123, v135, v111 row_shl:1 row_mask:0xf bank_mask:0xf bound_ctrl:1
	v_fmac_f32_dpp v116, v148, v156 row_shl:15 row_mask:0xf bank_mask:0xf bound_ctrl:1
	v_fmac_f32_dpp v117, v149, v157 row_shl:15 row_mask:0xf bank_mask:0xf bound_ctrl:1
	v_fmac_f32_dpp v118, v150, v158 row_shl:15 row_mask:0xf bank_mask:0xf bound_ctrl:1
	v_fmac_f32_dpp v119, v151, v159 row_shl:15 row_mask:0xf bank_mask:0xf bound_ctrl:1
	v_fmac_f32_dpp v120, v140, v104 row_shl:15 row_mask:0xf bank_mask:0xf bound_ctrl:1
	v_fmac_f32_dpp v121, v141, v105 row_shl:15 row_mask:0xf bank_mask:0xf bound_ctrl:1
	v_fmac_f32_dpp v122, v142, v106 row_shl:15 row_mask:0xf bank_mask:0xf bound_ctrl:1
	v_fmac_f32_dpp v123, v143, v107 row_shl:15 row_mask:0xf bank_mask:0xf bound_ctrl:1
	v_fmac_f32_dpp v116, v128, v160 row_shr:15 row_mask:0xf bank_mask:0xf bound_ctrl:1
	v_fmac_f32_dpp v117, v129, v161 row_shr:15 row_mask:0xf bank_mask:0xf bound_ctrl:1
	v_fmac_f32_dpp v118, v130, v162 row_shr:15 row_mask:0xf bank_mask:0xf bound_ctrl:1
	v_fmac_f32_dpp v119, v131, v163 row_shr:15 row_mask:0xf bank_mask:0xf bound_ctrl:1
	v_fmac_f32_dpp v120, v124, v108 row_shr:15 row_mask:0xf bank_mask:0xf bound_ctrl:1
	v_fmac_f32_dpp v121, v125, v109 row_shr:15 row_mask:0xf bank_mask:0xf bound_ctrl:1
	v_fmac_f32_dpp v122, v126, v110 row_shr:15 row_mask:0xf bank_mask:0xf bound_ctrl:1
	v_fmac_f32_dpp v123, v127, v111 row_shr:15 row_mask:0xf bank_mask:0xf bound_ctrl:1
	v_pk_mul_f32 v[48:49], v[116:117], s[0:1]
	v_pk_mul_f32 v[50:51], v[118:119], s[0:1]
	v_pk_mul_f32 v[52:53], v[116:117], v[120:121]
	v_pk_mul_f32 v[54:55], v[118:119], v[122:123]
	v_exp_f32_e32 v48, v48
	v_exp_f32_e32 v49, v49
	v_exp_f32_e32 v50, v50
	v_exp_f32_e32 v51, v51
	s_nop 0
	v_pk_add_f32 v[48:49], v[48:49], 1.0 op_sel_hi:[1,0]
	v_pk_add_f32 v[50:51], v[50:51], 1.0 op_sel_hi:[1,0]
	v_rcp_f32_e32 v48, v48
	v_rcp_f32_e32 v49, v49
	v_rcp_f32_e32 v50, v50
	v_rcp_f32_e32 v51, v51
	s_nop 0
	v_pk_mul_f32 v[52:53], v[52:53], v[48:49]
	v_pk_mul_f32 v[54:55], v[54:55], v[50:51]
	v_cvt_pk_bf16_f32 v252, v52, v53
	v_cvt_pk_bf16_f32 v253, v54, v55
	global_store_dwordx2 v[244:245], v[252:253], off
	v_lshl_add_u64 v[244:245], v[244:245], 0, s[2:3]
	v_mul_f32_e32 v116, v164, v128
	v_mul_f32_e32 v117, v165, v129
	v_mul_f32_e32 v118, v166, v130
	v_mul_f32_e32 v119, v167, v131
	v_mul_f32_e32 v120, v112, v124
	v_mul_f32_e32 v121, v113, v125
	v_mul_f32_e32 v122, v114, v126
	v_mul_f32_e32 v123, v115, v127
	v_fmac_f32_dpp v116, v128, v156 row_shr:1 row_mask:0xf bank_mask:0xf bound_ctrl:1
	v_fmac_f32_dpp v117, v129, v157 row_shr:1 row_mask:0xf bank_mask:0xf bound_ctrl:1
	v_fmac_f32_dpp v118, v130, v158 row_shr:1 row_mask:0xf bank_mask:0xf bound_ctrl:1
	v_fmac_f32_dpp v119, v131, v159 row_shr:1 row_mask:0xf bank_mask:0xf bound_ctrl:1
	v_fmac_f32_dpp v120, v124, v104 row_shr:1 row_mask:0xf bank_mask:0xf bound_ctrl:1
	v_fmac_f32_dpp v121, v125, v105 row_shr:1 row_mask:0xf bank_mask:0xf bound_ctrl:1
	v_fmac_f32_dpp v122, v126, v106 row_shr:1 row_mask:0xf bank_mask:0xf bound_ctrl:1
	v_fmac_f32_dpp v123, v127, v107 row_shr:1 row_mask:0xf bank_mask:0xf bound_ctrl:1
	v_fmac_f32_dpp v116, v128, v160 row_shl:1 row_mask:0xf bank_mask:0xf bound_ctrl:1
	v_fmac_f32_dpp v117, v129, v161 row_shl:1 row_mask:0xf bank_mask:0xf bound_ctrl:1
	v_fmac_f32_dpp v118, v130, v162 row_shl:1 row_mask:0xf bank_mask:0xf bound_ctrl:1
	v_fmac_f32_dpp v119, v131, v163 row_shl:1 row_mask:0xf bank_mask:0xf bound_ctrl:1
	v_fmac_f32_dpp v120, v124, v108 row_shl:1 row_mask:0xf bank_mask:0xf bound_ctrl:1
	v_fmac_f32_dpp v121, v125, v109 row_shl:1 row_mask:0xf bank_mask:0xf bound_ctrl:1
	v_fmac_f32_dpp v122, v126, v110 row_shl:1 row_mask:0xf bank_mask:0xf bound_ctrl:1
	v_fmac_f32_dpp v123, v127, v111 row_shl:1 row_mask:0xf bank_mask:0xf bound_ctrl:1
	v_fmac_f32_dpp v116, v136, v156 row_shl:15 row_mask:0xf bank_mask:0xf bound_ctrl:1
	v_fmac_f32_dpp v117, v137, v157 row_shl:15 row_mask:0xf bank_mask:0xf bound_ctrl:1
	v_fmac_f32_dpp v118, v138, v158 row_shl:15 row_mask:0xf bank_mask:0xf bound_ctrl:1
	v_fmac_f32_dpp v119, v139, v159 row_shl:15 row_mask:0xf bank_mask:0xf bound_ctrl:1
	v_fmac_f32_dpp v120, v132, v104 row_shl:15 row_mask:0xf bank_mask:0xf bound_ctrl:1
	v_fmac_f32_dpp v121, v133, v105 row_shl:15 row_mask:0xf bank_mask:0xf bound_ctrl:1
	v_fmac_f32_dpp v122, v134, v106 row_shl:15 row_mask:0xf bank_mask:0xf bound_ctrl:1
	v_fmac_f32_dpp v123, v135, v107 row_shl:15 row_mask:0xf bank_mask:0xf bound_ctrl:1
	v_pk_mul_f32 v[48:49], v[116:117], s[0:1]
	v_pk_mul_f32 v[50:51], v[118:119], s[0:1]
	v_pk_mul_f32 v[52:53], v[116:117], v[120:121]
	v_pk_mul_f32 v[54:55], v[118:119], v[122:123]
	v_exp_f32_e32 v48, v48
	v_exp_f32_e32 v49, v49
	v_exp_f32_e32 v50, v50
	v_exp_f32_e32 v51, v51
	v_cvt_pk_bf16_f32 v196, v128, v129
	v_cvt_pk_bf16_f32 v197, v130, v131
	v_cvt_pk_bf16_f32 v198, v124, v125
	v_cvt_pk_bf16_f32 v199, v126, v127
	v_pk_add_f32 v[48:49], v[48:49], 1.0 op_sel_hi:[1,0]
	v_pk_add_f32 v[50:51], v[50:51], 1.0 op_sel_hi:[1,0]
	v_rcp_f32_e32 v48, v48
	v_rcp_f32_e32 v49, v49
	v_rcp_f32_e32 v50, v50
	v_rcp_f32_e32 v51, v51
	s_nop 0
	v_pk_mul_f32 v[52:53], v[52:53], v[48:49]
	v_pk_mul_f32 v[54:55], v[54:55], v[50:51]
	v_cvt_pk_bf16_f32 v252, v52, v53
	v_cvt_pk_bf16_f32 v253, v54, v55
	s_and_saveexec_b64 vcc, s[8:9]
	global_store_dwordx2 v[244:245], v[252:253], off
	s_mov_b64 exec, vcc
	v_add_co_u32_e32 v250, vcc, 0xfffdf000, v250
	s_nop 1
	v_addc_co_u32_e32 v251, vcc, -1, v251, vcc
	v_add_co_u32_e32 v194, vcc, 0x1000, v250
	s_nop 1
	v_addc_co_u32_e32 v195, vcc, 0, v251, vcc
	s_and_saveexec_b64 vcc, s[14:15]
	global_store_dwordx2 v[250:251], v[196:197], off
	global_store_dwordx2 v[194:195], v[198:199], off offset:1536
	s_mov_b64 exec, vcc
	s_cmp_lg_u32 s83, 0
	s_cbranch_scc1 .Lup_n1
	v_add_co_u32_e32 v244, vcc, 0xb0000, v246
	s_nop 1
	v_addc_co_u32_e32 v245, vcc, 0, v247, vcc
	v_add_co_u32_e32 v250, vcc, 0x16000, v248
	s_nop 1
	v_addc_co_u32_e32 v251, vcc, 0, v249, vcc
	v_add_co_u32_e32 v194, vcc, 0x1000, v250
	s_nop 1
	v_addc_co_u32_e32 v195, vcc, 0, v251, vcc
	v_mul_f32_e32 v116, v164, v100
	v_mul_f32_e32 v117, v165, v101
	v_mul_f32_e32 v118, v166, v102
	v_mul_f32_e32 v119, v167, v103
	v_mul_f32_e32 v120, v112, v92
	v_mul_f32_e32 v121, v113, v93
	v_mul_f32_e32 v122, v114, v94
	v_mul_f32_e32 v123, v115, v95
	v_fmac_f32_dpp v116, v100, v156 row_shr:1 row_mask:0xf bank_mask:0xf bound_ctrl:1
	v_fmac_f32_dpp v117, v101, v157 row_shr:1 row_mask:0xf bank_mask:0xf bound_ctrl:1
	v_fmac_f32_dpp v118, v102, v158 row_shr:1 row_mask:0xf bank_mask:0xf bound_ctrl:1
	v_fmac_f32_dpp v119, v103, v159 row_shr:1 row_mask:0xf bank_mask:0xf bound_ctrl:1
	v_fmac_f32_dpp v120, v92, v104 row_shr:1 row_mask:0xf bank_mask:0xf bound_ctrl:1
	v_fmac_f32_dpp v121, v93, v105 row_shr:1 row_mask:0xf bank_mask:0xf bound_ctrl:1
	v_fmac_f32_dpp v122, v94, v106 row_shr:1 row_mask:0xf bank_mask:0xf bound_ctrl:1
	v_fmac_f32_dpp v123, v95, v107 row_shr:1 row_mask:0xf bank_mask:0xf bound_ctrl:1
	v_fmac_f32_dpp v116, v100, v160 row_shl:1 row_mask:0xf bank_mask:0xf bound_ctrl:1
	v_fmac_f32_dpp v117, v101, v161 row_shl:1 row_mask:0xf bank_mask:0xf bound_ctrl:1
	v_fmac_f32_dpp v118, v102, v162 row_shl:1 row_mask:0xf bank_mask:0xf bound_ctrl:1
	v_fmac_f32_dpp v119, v103, v163 row_shl:1 row_mask:0xf bank_mask:0xf bound_ctrl:1
	v_fmac_f32_dpp v120, v92, v108 row_shl:1 row_mask:0xf bank_mask:0xf bound_ctrl:1
	v_fmac_f32_dpp v121, v93, v109 row_shl:1 row_mask:0xf bank_mask:0xf bound_ctrl:1
	v_fmac_f32_dpp v122, v94, v110 row_shl:1 row_mask:0xf bank_mask:0xf bound_ctrl:1
	v_fmac_f32_dpp v123, v95, v111 row_shl:1 row_mask:0xf bank_mask:0xf bound_ctrl:1
	v_fmac_f32_dpp v116, v96, v160 row_shr:15 row_mask:0xf bank_mask:0xf bound_ctrl:1
	v_fmac_f32_dpp v117, v97, v161 row_shr:15 row_mask:0xf bank_mask:0xf bound_ctrl:1
	v_fmac_f32_dpp v118, v98, v162 row_shr:15 row_mask:0xf bank_mask:0xf bound_ctrl:1
	v_fmac_f32_dpp v119, v99, v163 row_shr:15 row_mask:0xf bank_mask:0xf bound_ctrl:1
	v_fmac_f32_dpp v120, v88, v108 row_shr:15 row_mask:0xf bank_mask:0xf bound_ctrl:1
	v_fmac_f32_dpp v121, v89, v109 row_shr:15 row_mask:0xf bank_mask:0xf bound_ctrl:1
	v_fmac_f32_dpp v122, v90, v110 row_shr:15 row_mask:0xf bank_mask:0xf bound_ctrl:1
	v_fmac_f32_dpp v123, v91, v111 row_shr:15 row_mask:0xf bank_mask:0xf bound_ctrl:1
	v_pk_mul_f32 v[48:49], v[116:117], s[0:1]
	v_pk_mul_f32 v[50:51], v[118:119], s[0:1]
	v_pk_mul_f32 v[52:53], v[116:117], v[120:121]
	v_pk_mul_f32 v[54:55], v[118:119], v[122:123]
	v_exp_f32_e32 v48, v48
	v_exp_f32_e32 v49, v49
	v_exp_f32_e32 v50, v50
	v_exp_f32_e32 v51, v51
	v_cvt_pk_bf16_f32 v196, v100, v101
	v_cvt_pk_bf16_f32 v197, v102, v103
	v_cvt_pk_bf16_f32 v198, v92, v93
	v_cvt_pk_bf16_f32 v199, v94, v95
	v_pk_add_f32 v[48:49], v[48:49], 1.0 op_sel_hi:[1,0]
	v_pk_add_f32 v[50:51], v[50:51], 1.0 op_sel_hi:[1,0]
	v_rcp_f32_e32 v48, v48
	v_rcp_f32_e32 v49, v49
	v_rcp_f32_e32 v50, v50
	v_rcp_f32_e32 v51, v51
	s_nop 0
	v_pk_mul_f32 v[52:53], v[52:53], v[48:49]
	v_pk_mul_f32 v[54:55], v[54:55], v[50:51]
	v_cvt_pk_bf16_f32 v252, v52, v53
	v_cvt_pk_bf16_f32 v253, v54, v55
	s_and_saveexec_b64 vcc, s[10:11]
	global_store_dwordx2 v[244:245], v[252:253], off
	s_mov_b64 exec, vcc
	s_and_saveexec_b64 vcc, s[12:13]
	global_store_dwordx2 v[250:251], v[196:197], off
	global_store_dwordx2 v[194:195], v[198:199], off offset:1536
	s_mov_b64 exec, vcc
	v_lshl_add_u64 v[244:245], v[244:245], 0, s[2:3]
	v_mul_f32_e32 v116, v164, v96
	v_mul_f32_e32 v117, v165, v97
	v_mul_f32_e32 v118, v166, v98
	v_mul_f32_e32 v119, v167, v99
	v_mul_f32_e32 v120, v112, v88
	v_mul_f32_e32 v121, v113, v89
	v_mul_f32_e32 v122, v114, v90
	v_mul_f32_e32 v123, v115, v91
	v_fmac_f32_dpp v116, v96, v156 row_shr:1 row_mask:0xf bank_mask:0xf bound_ctrl:1
	v_fmac_f32_dpp v117, v97, v157 row_shr:1 row_mask:0xf bank_mask:0xf bound_ctrl:1
	v_fmac_f32_dpp v118, v98, v158 row_shr:1 row_mask:0xf bank_mask:0xf bound_ctrl:1
	v_fmac_f32_dpp v119, v99, v159 row_shr:1 row_mask:0xf bank_mask:0xf bound_ctrl:1
	v_fmac_f32_dpp v120, v88, v104 row_shr:1 row_mask:0xf bank_mask:0xf bound_ctrl:1
	v_fmac_f32_dpp v121, v89, v105 row_shr:1 row_mask:0xf bank_mask:0xf bound_ctrl:1
	v_fmac_f32_dpp v122, v90, v106 row_shr:1 row_mask:0xf bank_mask:0xf bound_ctrl:1
	v_fmac_f32_dpp v123, v91, v107 row_shr:1 row_mask:0xf bank_mask:0xf bound_ctrl:1
	v_fmac_f32_dpp v116, v96, v160 row_shl:1 row_mask:0xf bank_mask:0xf bound_ctrl:1
	v_fmac_f32_dpp v117, v97, v161 row_shl:1 row_mask:0xf bank_mask:0xf bound_ctrl:1
	v_fmac_f32_dpp v118, v98, v162 row_shl:1 row_mask:0xf bank_mask:0xf bound_ctrl:1
	v_fmac_f32_dpp v119, v99, v163 row_shl:1 row_mask:0xf bank_mask:0xf bound_ctrl:1
	v_fmac_f32_dpp v120, v88, v108 row_shl:1 row_mask:0xf bank_mask:0xf bound_ctrl:1
	v_fmac_f32_dpp v121, v89, v109 row_shl:1 row_mask:0xf bank_mask:0xf bound_ctrl:1
	v_fmac_f32_dpp v122, v90, v110 row_shl:1 row_mask:0xf bank_mask:0xf bound_ctrl:1
	v_fmac_f32_dpp v123, v91, v111 row_shl:1 row_mask:0xf bank_mask:0xf bound_ctrl:1
	v_fmac_f32_dpp v116, v100, v156 row_shl:15 row_mask:0xf bank_mask:0xf bound_ctrl:1
	v_fmac_f32_dpp v117, v101, v157 row_shl:15 row_mask:0xf bank_mask:0xf bound_ctrl:1
	v_fmac_f32_dpp v118, v102, v158 row_shl:15 row_mask:0xf bank_mask:0xf bound_ctrl:1
	v_fmac_f32_dpp v119, v103, v159 row_shl:15 row_mask:0xf bank_mask:0xf bound_ctrl:1
	v_fmac_f32_dpp v120, v92, v104 row_shl:15 row_mask:0xf bank_mask:0xf bound_ctrl:1
	v_fmac_f32_dpp v121, v93, v105 row_shl:15 row_mask:0xf bank_mask:0xf bound_ctrl:1
	v_fmac_f32_dpp v122, v94, v106 row_shl:15 row_mask:0xf bank_mask:0xf bound_ctrl:1
	v_fmac_f32_dpp v123, v95, v107 row_shl:15 row_mask:0xf bank_mask:0xf bound_ctrl:1
	v_fmac_f32_dpp v116, v84, v160 row_shr:15 row_mask:0xf bank_mask:0xf bound_ctrl:1
	v_fmac_f32_dpp v117, v85, v161 row_shr:15 row_mask:0xf bank_mask:0xf bound_ctrl:1
	v_fmac_f32_dpp v118, v86, v162 row_shr:15 row_mask:0xf bank_mask:0xf bound_ctrl:1
	v_fmac_f32_dpp v119, v87, v163 row_shr:15 row_mask:0xf bank_mask:0xf bound_ctrl:1
	v_fmac_f32_dpp v120, v80, v108 row_shr:15 row_mask:0xf bank_mask:0xf bound_ctrl:1
	v_fmac_f32_dpp v121, v81, v109 row_shr:15 row_mask:0xf bank_mask:0xf bound_ctrl:1
	v_fmac_f32_dpp v122, v82, v110 row_shr:15 row_mask:0xf bank_mask:0xf bound_ctrl:1
	v_fmac_f32_dpp v123, v83, v111 row_shr:15 row_mask:0xf bank_mask:0xf bound_ctrl:1
	v_pk_mul_f32 v[48:49], v[116:117], s[0:1]
	v_pk_mul_f32 v[50:51], v[118:119], s[0:1]
	v_pk_mul_f32 v[52:53], v[116:117], v[120:121]
	v_pk_mul_f32 v[54:55], v[118:119], v[122:123]
	v_exp_f32_e32 v48, v48
	v_exp_f32_e32 v49, v49
	v_exp_f32_e32 v50, v50
	v_exp_f32_e32 v51, v51
	s_nop 0
	v_pk_add_f32 v[48:49], v[48:49], 1.0 op_sel_hi:[1,0]
	v_pk_add_f32 v[50:51], v[50:51], 1.0 op_sel_hi:[1,0]
	v_rcp_f32_e32 v48, v48
	v_rcp_f32_e32 v49, v49
	v_rcp_f32_e32 v50, v50
	v_rcp_f32_e32 v51, v51
	s_nop 0
	v_pk_mul_f32 v[52:53], v[52:53], v[48:49]
	v_pk_mul_f32 v[54:55], v[54:55], v[50:51]
	v_cvt_pk_bf16_f32 v252, v52, v53
	v_cvt_pk_bf16_f32 v253, v54, v55
	global_store_dwordx2 v[244:245], v[252:253], off
	v_lshl_add_u64 v[244:245], v[244:245], 0, s[2:3]
	v_mul_f32_e32 v116, v164, v84
	v_mul_f32_e32 v117, v165, v85
	v_mul_f32_e32 v118, v166, v86
	v_mul_f32_e32 v119, v167, v87
	v_mul_f32_e32 v120, v112, v80
	v_mul_f32_e32 v121, v113, v81
	v_mul_f32_e32 v122, v114, v82
	v_mul_f32_e32 v123, v115, v83
	v_fmac_f32_dpp v116, v84, v156 row_shr:1 row_mask:0xf bank_mask:0xf bound_ctrl:1
	v_fmac_f32_dpp v117, v85, v157 row_shr:1 row_mask:0xf bank_mask:0xf bound_ctrl:1
	v_fmac_f32_dpp v118, v86, v158 row_shr:1 row_mask:0xf bank_mask:0xf bound_ctrl:1
	v_fmac_f32_dpp v119, v87, v159 row_shr:1 row_mask:0xf bank_mask:0xf bound_ctrl:1
	v_fmac_f32_dpp v120, v80, v104 row_shr:1 row_mask:0xf bank_mask:0xf bound_ctrl:1
	v_fmac_f32_dpp v121, v81, v105 row_shr:1 row_mask:0xf bank_mask:0xf bound_ctrl:1
	v_fmac_f32_dpp v122, v82, v106 row_shr:1 row_mask:0xf bank_mask:0xf bound_ctrl:1
	v_fmac_f32_dpp v123, v83, v107 row_shr:1 row_mask:0xf bank_mask:0xf bound_ctrl:1
	v_fmac_f32_dpp v116, v84, v160 row_shl:1 row_mask:0xf bank_mask:0xf bound_ctrl:1
	v_fmac_f32_dpp v117, v85, v161 row_shl:1 row_mask:0xf bank_mask:0xf bound_ctrl:1
	v_fmac_f32_dpp v118, v86, v162 row_shl:1 row_mask:0xf bank_mask:0xf bound_ctrl:1
	v_fmac_f32_dpp v119, v87, v163 row_shl:1 row_mask:0xf bank_mask:0xf bound_ctrl:1
	v_fmac_f32_dpp v120, v80, v108 row_shl:1 row_mask:0xf bank_mask:0xf bound_ctrl:1
	v_fmac_f32_dpp v121, v81, v109 row_shl:1 row_mask:0xf bank_mask:0xf bound_ctrl:1
	v_fmac_f32_dpp v122, v82, v110 row_shl:1 row_mask:0xf bank_mask:0xf bound_ctrl:1
	v_fmac_f32_dpp v123, v83, v111 row_shl:1 row_mask:0xf bank_mask:0xf bound_ctrl:1
	v_fmac_f32_dpp v116, v96, v156 row_shl:15 row_mask:0xf bank_mask:0xf bound_ctrl:1
	v_fmac_f32_dpp v117, v97, v157 row_shl:15 row_mask:0xf bank_mask:0xf bound_ctrl:1
	v_fmac_f32_dpp v118, v98, v158 row_shl:15 row_mask:0xf bank_mask:0xf bound_ctrl:1
	v_fmac_f32_dpp v119, v99, v159 row_shl:15 row_mask:0xf bank_mask:0xf bound_ctrl:1
	v_fmac_f32_dpp v120, v88, v104 row_shl:15 row_mask:0xf bank_mask:0xf bound_ctrl:1
	v_fmac_f32_dpp v121, v89, v105 row_shl:15 row_mask:0xf bank_mask:0xf bound_ctrl:1
	v_fmac_f32_dpp v122, v90, v106 row_shl:15 row_mask:0xf bank_mask:0xf bound_ctrl:1
	v_fmac_f32_dpp v123, v91, v107 row_shl:15 row_mask:0xf bank_mask:0xf bound_ctrl:1
	v_fmac_f32_dpp v116, v76, v160 row_shr:15 row_mask:0xf bank_mask:0xf bound_ctrl:1
	v_fmac_f32_dpp v117, v77, v161 row_shr:15 row_mask:0xf bank_mask:0xf bound_ctrl:1
	v_fmac_f32_dpp v118, v78, v162 row_shr:15 row_mask:0xf bank_mask:0xf bound_ctrl:1
	v_fmac_f32_dpp v119, v79, v163 row_shr:15 row_mask:0xf bank_mask:0xf bound_ctrl:1
	v_fmac_f32_dpp v120, v72, v108 row_shr:15 row_mask:0xf bank_mask:0xf bound_ctrl:1
	v_fmac_f32_dpp v121, v73, v109 row_shr:15 row_mask:0xf bank_mask:0xf bound_ctrl:1
	v_fmac_f32_dpp v122, v74, v110 row_shr:15 row_mask:0xf bank_mask:0xf bound_ctrl:1
	v_fmac_f32_dpp v123, v75, v111 row_shr:15 row_mask:0xf bank_mask:0xf bound_ctrl:1
	v_pk_mul_f32 v[48:49], v[116:117], s[0:1]
	v_pk_mul_f32 v[50:51], v[118:119], s[0:1]
	v_pk_mul_f32 v[52:53], v[116:117], v[120:121]
	v_pk_mul_f32 v[54:55], v[118:119], v[122:123]
	v_exp_f32_e32 v48, v48
	v_exp_f32_e32 v49, v49
	v_exp_f32_e32 v50, v50
	v_exp_f32_e32 v51, v51
	s_nop 0
	v_pk_add_f32 v[48:49], v[48:49], 1.0 op_sel_hi:[1,0]
	v_pk_add_f32 v[50:51], v[50:51], 1.0 op_sel_hi:[1,0]
	v_rcp_f32_e32 v48, v48
	v_rcp_f32_e32 v49, v49
	v_rcp_f32_e32 v50, v50
	v_rcp_f32_e32 v51, v51
	s_nop 0
	v_pk_mul_f32 v[52:53], v[52:53], v[48:49]
	v_pk_mul_f32 v[54:55], v[54:55], v[50:51]
	v_cvt_pk_bf16_f32 v252, v52, v53
	v_cvt_pk_bf16_f32 v253, v54, v55
	global_store_dwordx2 v[244:245], v[252:253], off
	v_lshl_add_u64 v[244:245], v[244:245], 0, s[2:3]
	v_mul_f32_e32 v116, v164, v76
	v_mul_f32_e32 v117, v165, v77
	v_mul_f32_e32 v118, v166, v78
	v_mul_f32_e32 v119, v167, v79
	v_mul_f32_e32 v120, v112, v72
	v_mul_f32_e32 v121, v113, v73
	v_mul_f32_e32 v122, v114, v74
	v_mul_f32_e32 v123, v115, v75
	v_fmac_f32_dpp v116, v76, v156 row_shr:1 row_mask:0xf bank_mask:0xf bound_ctrl:1
	v_fmac_f32_dpp v117, v77, v157 row_shr:1 row_mask:0xf bank_mask:0xf bound_ctrl:1
	v_fmac_f32_dpp v118, v78, v158 row_shr:1 row_mask:0xf bank_mask:0xf bound_ctrl:1
	v_fmac_f32_dpp v119, v79, v159 row_shr:1 row_mask:0xf bank_mask:0xf bound_ctrl:1
	v_fmac_f32_dpp v120, v72, v104 row_shr:1 row_mask:0xf bank_mask:0xf bound_ctrl:1
	v_fmac_f32_dpp v121, v73, v105 row_shr:1 row_mask:0xf bank_mask:0xf bound_ctrl:1
	v_fmac_f32_dpp v122, v74, v106 row_shr:1 row_mask:0xf bank_mask:0xf bound_ctrl:1
	v_fmac_f32_dpp v123, v75, v107 row_shr:1 row_mask:0xf bank_mask:0xf bound_ctrl:1
	v_fmac_f32_dpp v116, v76, v160 row_shl:1 row_mask:0xf bank_mask:0xf bound_ctrl:1
	v_fmac_f32_dpp v117, v77, v161 row_shl:1 row_mask:0xf bank_mask:0xf bound_ctrl:1
	v_fmac_f32_dpp v118, v78, v162 row_shl:1 row_mask:0xf bank_mask:0xf bound_ctrl:1
	v_fmac_f32_dpp v119, v79, v163 row_shl:1 row_mask:0xf bank_mask:0xf bound_ctrl:1
	v_fmac_f32_dpp v120, v72, v108 row_shl:1 row_mask:0xf bank_mask:0xf bound_ctrl:1
	v_fmac_f32_dpp v121, v73, v109 row_shl:1 row_mask:0xf bank_mask:0xf bound_ctrl:1
	v_fmac_f32_dpp v122, v74, v110 row_shl:1 row_mask:0xf bank_mask:0xf bound_ctrl:1
	v_fmac_f32_dpp v123, v75, v111 row_shl:1 row_mask:0xf bank_mask:0xf bound_ctrl:1
	v_fmac_f32_dpp v116, v84, v156 row_shl:15 row_mask:0xf bank_mask:0xf bound_ctrl:1
	v_fmac_f32_dpp v117, v85, v157 row_shl:15 row_mask:0xf bank_mask:0xf bound_ctrl:1
	v_fmac_f32_dpp v118, v86, v158 row_shl:15 row_mask:0xf bank_mask:0xf bound_ctrl:1
	v_fmac_f32_dpp v119, v87, v159 row_shl:15 row_mask:0xf bank_mask:0xf bound_ctrl:1
	v_fmac_f32_dpp v120, v80, v104 row_shl:15 row_mask:0xf bank_mask:0xf bound_ctrl:1
	v_fmac_f32_dpp v121, v81, v105 row_shl:15 row_mask:0xf bank_mask:0xf bound_ctrl:1
	v_fmac_f32_dpp v122, v82, v106 row_shl:15 row_mask:0xf bank_mask:0xf bound_ctrl:1
	v_fmac_f32_dpp v123, v83, v107 row_shl:15 row_mask:0xf bank_mask:0xf bound_ctrl:1
	v_pk_mul_f32 v[48:49], v[116:117], s[0:1]
	v_pk_mul_f32 v[50:51], v[118:119], s[0:1]
	v_pk_mul_f32 v[52:53], v[116:117], v[120:121]
	v_pk_mul_f32 v[54:55], v[118:119], v[122:123]
	v_exp_f32_e32 v48, v48
	v_exp_f32_e32 v49, v49
	v_exp_f32_e32 v50, v50
	v_exp_f32_e32 v51, v51
	v_cvt_pk_bf16_f32 v196, v76, v77
	v_cvt_pk_bf16_f32 v197, v78, v79
	v_cvt_pk_bf16_f32 v198, v72, v73
	v_cvt_pk_bf16_f32 v199, v74, v75
	v_pk_add_f32 v[48:49], v[48:49], 1.0 op_sel_hi:[1,0]
	v_pk_add_f32 v[50:51], v[50:51], 1.0 op_sel_hi:[1,0]
	v_rcp_f32_e32 v48, v48
	v_rcp_f32_e32 v49, v49
	v_rcp_f32_e32 v50, v50
	v_rcp_f32_e32 v51, v51
	s_nop 0
	v_pk_mul_f32 v[52:53], v[52:53], v[48:49]
	v_pk_mul_f32 v[54:55], v[54:55], v[50:51]
	v_cvt_pk_bf16_f32 v252, v52, v53
	v_cvt_pk_bf16_f32 v253, v54, v55
	s_and_saveexec_b64 vcc, s[8:9]
	global_store_dwordx2 v[244:245], v[252:253], off
	s_mov_b64 exec, vcc
	v_add_co_u32_e32 v250, vcc, 0xfffdf000, v250
	s_nop 1
	v_addc_co_u32_e32 v251, vcc, -1, v251, vcc
	v_add_co_u32_e32 v194, vcc, 0x1000, v250
	s_nop 1
	v_addc_co_u32_e32 v195, vcc, 0, v251, vcc
	s_and_saveexec_b64 vcc, s[14:15]
	global_store_dwordx2 v[250:251], v[196:197], off
	global_store_dwordx2 v[194:195], v[198:199], off offset:1536
	s_mov_b64 exec, vcc
.Lup_n1:
	v_mov_b32_e32 v244, v246
	v_mov_b32_e32 v245, v247
	v_mov_b32_e32 v250, v248
	v_mov_b32_e32 v251, v249
	v_add_co_u32_e32 v194, vcc, 0x1000, v250
	s_nop 1
	v_addc_co_u32_e32 v195, vcc, 0, v251, vcc
	v_mul_f32_e32 v116, v208, v68
	v_mul_f32_e32 v117, v209, v69
	v_mul_f32_e32 v118, v210, v70
	v_mul_f32_e32 v119, v211, v71
	v_mul_f32_e32 v120, v212, v60
	v_mul_f32_e32 v121, v213, v61
	v_mul_f32_e32 v122, v214, v62
	v_mul_f32_e32 v123, v215, v63
	v_fmac_f32_dpp v116, v68, v220 row_shr:1 row_mask:0xf bank_mask:0xf bound_ctrl:1
	v_fmac_f32_dpp v117, v69, v221 row_shr:1 row_mask:0xf bank_mask:0xf bound_ctrl:1
	v_fmac_f32_dpp v118, v70, v222 row_shr:1 row_mask:0xf bank_mask:0xf bound_ctrl:1
	v_fmac_f32_dpp v119, v71, v223 row_shr:1 row_mask:0xf bank_mask:0xf bound_ctrl:1
	v_fmac_f32_dpp v120, v60, v204 row_shr:1 row_mask:0xf bank_mask:0xf bound_ctrl:1
	v_fmac_f32_dpp v121, v61, v205 row_shr:1 row_mask:0xf bank_mask:0xf bound_ctrl:1
	v_fmac_f32_dpp v122, v62, v206 row_shr:1 row_mask:0xf bank_mask:0xf bound_ctrl:1
	v_fmac_f32_dpp v123, v63, v207 row_shr:1 row_mask:0xf bank_mask:0xf bound_ctrl:1
	v_fmac_f32_dpp v116, v68, v216 row_shl:1 row_mask:0xf bank_mask:0xf bound_ctrl:1
	v_fmac_f32_dpp v117, v69, v217 row_shl:1 row_mask:0xf bank_mask:0xf bound_ctrl:1
	v_fmac_f32_dpp v118, v70, v218 row_shl:1 row_mask:0xf bank_mask:0xf bound_ctrl:1
	v_fmac_f32_dpp v119, v71, v219 row_shl:1 row_mask:0xf bank_mask:0xf bound_ctrl:1
	v_fmac_f32_dpp v120, v60, v200 row_shl:1 row_mask:0xf bank_mask:0xf bound_ctrl:1
	v_fmac_f32_dpp v121, v61, v201 row_shl:1 row_mask:0xf bank_mask:0xf bound_ctrl:1
	v_fmac_f32_dpp v122, v62, v202 row_shl:1 row_mask:0xf bank_mask:0xf bound_ctrl:1
	v_fmac_f32_dpp v123, v63, v203 row_shl:1 row_mask:0xf bank_mask:0xf bound_ctrl:1
	v_fmac_f32_dpp v116, v64, v216 row_shr:15 row_mask:0xf bank_mask:0xf bound_ctrl:1
	v_fmac_f32_dpp v117, v65, v217 row_shr:15 row_mask:0xf bank_mask:0xf bound_ctrl:1
	v_fmac_f32_dpp v118, v66, v218 row_shr:15 row_mask:0xf bank_mask:0xf bound_ctrl:1
	v_fmac_f32_dpp v119, v67, v219 row_shr:15 row_mask:0xf bank_mask:0xf bound_ctrl:1
	v_fmac_f32_dpp v120, v56, v200 row_shr:15 row_mask:0xf bank_mask:0xf bound_ctrl:1
	v_fmac_f32_dpp v121, v57, v201 row_shr:15 row_mask:0xf bank_mask:0xf bound_ctrl:1
	v_fmac_f32_dpp v122, v58, v202 row_shr:15 row_mask:0xf bank_mask:0xf bound_ctrl:1
	v_fmac_f32_dpp v123, v59, v203 row_shr:15 row_mask:0xf bank_mask:0xf bound_ctrl:1
	v_pk_mul_f32 v[48:49], v[116:117], s[0:1]
	v_pk_mul_f32 v[50:51], v[118:119], s[0:1]
	v_pk_mul_f32 v[52:53], v[116:117], v[120:121]
	v_pk_mul_f32 v[54:55], v[118:119], v[122:123]
	v_exp_f32_e32 v48, v48
	v_exp_f32_e32 v49, v49
	v_exp_f32_e32 v50, v50
	v_exp_f32_e32 v51, v51
	v_cvt_pk_bf16_f32 v196, v68, v69
	v_cvt_pk_bf16_f32 v197, v70, v71
	v_cvt_pk_bf16_f32 v198, v60, v61
	v_cvt_pk_bf16_f32 v199, v62, v63
	v_pk_add_f32 v[48:49], v[48:49], 1.0 op_sel_hi:[1,0]
	v_pk_add_f32 v[50:51], v[50:51], 1.0 op_sel_hi:[1,0]
	v_rcp_f32_e32 v48, v48
	v_rcp_f32_e32 v49, v49
	v_rcp_f32_e32 v50, v50
	v_rcp_f32_e32 v51, v51
	s_nop 0
	v_pk_mul_f32 v[52:53], v[52:53], v[48:49]
	v_pk_mul_f32 v[54:55], v[54:55], v[50:51]
	v_cvt_pk_bf16_f32 v252, v52, v53
	v_cvt_pk_bf16_f32 v253, v54, v55
	s_and_saveexec_b64 vcc, s[10:11]
	global_store_dwordx2 v[244:245], v[252:253], off offset:8
	s_mov_b64 exec, vcc
	s_and_saveexec_b64 vcc, s[12:13]
	global_store_dwordx2 v[250:251], v[196:197], off offset:8
	global_store_dwordx2 v[194:195], v[198:199], off offset:1544
	s_mov_b64 exec, vcc
	v_lshl_add_u64 v[244:245], v[244:245], 0, s[2:3]
	v_mul_f32_e32 v116, v208, v64
	v_mul_f32_e32 v117, v209, v65
	v_mul_f32_e32 v118, v210, v66
	v_mul_f32_e32 v119, v211, v67
	v_mul_f32_e32 v120, v212, v56
	v_mul_f32_e32 v121, v213, v57
	v_mul_f32_e32 v122, v214, v58
	v_mul_f32_e32 v123, v215, v59
	v_fmac_f32_dpp v116, v64, v220 row_shr:1 row_mask:0xf bank_mask:0xf bound_ctrl:1
	v_fmac_f32_dpp v117, v65, v221 row_shr:1 row_mask:0xf bank_mask:0xf bound_ctrl:1
	v_fmac_f32_dpp v118, v66, v222 row_shr:1 row_mask:0xf bank_mask:0xf bound_ctrl:1
	v_fmac_f32_dpp v119, v67, v223 row_shr:1 row_mask:0xf bank_mask:0xf bound_ctrl:1
	v_fmac_f32_dpp v120, v56, v204 row_shr:1 row_mask:0xf bank_mask:0xf bound_ctrl:1
	v_fmac_f32_dpp v121, v57, v205 row_shr:1 row_mask:0xf bank_mask:0xf bound_ctrl:1
	v_fmac_f32_dpp v122, v58, v206 row_shr:1 row_mask:0xf bank_mask:0xf bound_ctrl:1
	v_fmac_f32_dpp v123, v59, v207 row_shr:1 row_mask:0xf bank_mask:0xf bound_ctrl:1
	v_fmac_f32_dpp v116, v64, v216 row_shl:1 row_mask:0xf bank_mask:0xf bound_ctrl:1
	v_fmac_f32_dpp v117, v65, v217 row_shl:1 row_mask:0xf bank_mask:0xf bound_ctrl:1
	v_fmac_f32_dpp v118, v66, v218 row_shl:1 row_mask:0xf bank_mask:0xf bound_ctrl:1
	v_fmac_f32_dpp v119, v67, v219 row_shl:1 row_mask:0xf bank_mask:0xf bound_ctrl:1
	v_fmac_f32_dpp v120, v56, v200 row_shl:1 row_mask:0xf bank_mask:0xf bound_ctrl:1
	v_fmac_f32_dpp v121, v57, v201 row_shl:1 row_mask:0xf bank_mask:0xf bound_ctrl:1
	v_fmac_f32_dpp v122, v58, v202 row_shl:1 row_mask:0xf bank_mask:0xf bound_ctrl:1
	v_fmac_f32_dpp v123, v59, v203 row_shl:1 row_mask:0xf bank_mask:0xf bound_ctrl:1
	v_fmac_f32_dpp v116, v68, v220 row_shl:15 row_mask:0xf bank_mask:0xf bound_ctrl:1
	v_fmac_f32_dpp v117, v69, v221 row_shl:15 row_mask:0xf bank_mask:0xf bound_ctrl:1
	v_fmac_f32_dpp v118, v70, v222 row_shl:15 row_mask:0xf bank_mask:0xf bound_ctrl:1
	v_fmac_f32_dpp v119, v71, v223 row_shl:15 row_mask:0xf bank_mask:0xf bound_ctrl:1
	v_fmac_f32_dpp v120, v60, v204 row_shl:15 row_mask:0xf bank_mask:0xf bound_ctrl:1
	v_fmac_f32_dpp v121, v61, v205 row_shl:15 row_mask:0xf bank_mask:0xf bound_ctrl:1
	v_fmac_f32_dpp v122, v62, v206 row_shl:15 row_mask:0xf bank_mask:0xf bound_ctrl:1
	v_fmac_f32_dpp v123, v63, v207 row_shl:15 row_mask:0xf bank_mask:0xf bound_ctrl:1
	v_fmac_f32_dpp v116, v44, v216 row_shr:15 row_mask:0xf bank_mask:0xf bound_ctrl:1
	v_fmac_f32_dpp v117, v45, v217 row_shr:15 row_mask:0xf bank_mask:0xf bound_ctrl:1
	v_fmac_f32_dpp v118, v46, v218 row_shr:15 row_mask:0xf bank_mask:0xf bound_ctrl:1
	v_fmac_f32_dpp v119, v47, v219 row_shr:15 row_mask:0xf bank_mask:0xf bound_ctrl:1
	v_fmac_f32_dpp v120, v36, v200 row_shr:15 row_mask:0xf bank_mask:0xf bound_ctrl:1
	v_fmac_f32_dpp v121, v37, v201 row_shr:15 row_mask:0xf bank_mask:0xf bound_ctrl:1
	v_fmac_f32_dpp v122, v38, v202 row_shr:15 row_mask:0xf bank_mask:0xf bound_ctrl:1
	v_fmac_f32_dpp v123, v39, v203 row_shr:15 row_mask:0xf bank_mask:0xf bound_ctrl:1
	v_pk_mul_f32 v[48:49], v[116:117], s[0:1]
	v_pk_mul_f32 v[50:51], v[118:119], s[0:1]
	v_pk_mul_f32 v[52:53], v[116:117], v[120:121]
	v_pk_mul_f32 v[54:55], v[118:119], v[122:123]
	v_exp_f32_e32 v48, v48
	v_exp_f32_e32 v49, v49
	v_exp_f32_e32 v50, v50
	v_exp_f32_e32 v51, v51
	s_nop 0
	v_pk_add_f32 v[48:49], v[48:49], 1.0 op_sel_hi:[1,0]
	v_pk_add_f32 v[50:51], v[50:51], 1.0 op_sel_hi:[1,0]
	v_rcp_f32_e32 v48, v48
	v_rcp_f32_e32 v49, v49
	v_rcp_f32_e32 v50, v50
	v_rcp_f32_e32 v51, v51
	s_nop 0
	v_pk_mul_f32 v[52:53], v[52:53], v[48:49]
	v_pk_mul_f32 v[54:55], v[54:55], v[50:51]
	v_cvt_pk_bf16_f32 v252, v52, v53
	v_cvt_pk_bf16_f32 v253, v54, v55
	global_store_dwordx2 v[244:245], v[252:253], off offset:8
	v_lshl_add_u64 v[244:245], v[244:245], 0, s[2:3]
	v_mul_f32_e32 v116, v208, v44
	v_mul_f32_e32 v117, v209, v45
	v_mul_f32_e32 v118, v210, v46
	v_mul_f32_e32 v119, v211, v47
	v_mul_f32_e32 v120, v212, v36
	v_mul_f32_e32 v121, v213, v37
	v_mul_f32_e32 v122, v214, v38
	v_mul_f32_e32 v123, v215, v39
	v_fmac_f32_dpp v116, v44, v220 row_shr:1 row_mask:0xf bank_mask:0xf bound_ctrl:1
	v_fmac_f32_dpp v117, v45, v221 row_shr:1 row_mask:0xf bank_mask:0xf bound_ctrl:1
	v_fmac_f32_dpp v118, v46, v222 row_shr:1 row_mask:0xf bank_mask:0xf bound_ctrl:1
	v_fmac_f32_dpp v119, v47, v223 row_shr:1 row_mask:0xf bank_mask:0xf bound_ctrl:1
	v_fmac_f32_dpp v120, v36, v204 row_shr:1 row_mask:0xf bank_mask:0xf bound_ctrl:1
	v_fmac_f32_dpp v121, v37, v205 row_shr:1 row_mask:0xf bank_mask:0xf bound_ctrl:1
	v_fmac_f32_dpp v122, v38, v206 row_shr:1 row_mask:0xf bank_mask:0xf bound_ctrl:1
	v_fmac_f32_dpp v123, v39, v207 row_shr:1 row_mask:0xf bank_mask:0xf bound_ctrl:1
	v_fmac_f32_dpp v116, v44, v216 row_shl:1 row_mask:0xf bank_mask:0xf bound_ctrl:1
	v_fmac_f32_dpp v117, v45, v217 row_shl:1 row_mask:0xf bank_mask:0xf bound_ctrl:1
	v_fmac_f32_dpp v118, v46, v218 row_shl:1 row_mask:0xf bank_mask:0xf bound_ctrl:1
	v_fmac_f32_dpp v119, v47, v219 row_shl:1 row_mask:0xf bank_mask:0xf bound_ctrl:1
	v_fmac_f32_dpp v120, v36, v200 row_shl:1 row_mask:0xf bank_mask:0xf bound_ctrl:1
	v_fmac_f32_dpp v121, v37, v201 row_shl:1 row_mask:0xf bank_mask:0xf bound_ctrl:1
	v_fmac_f32_dpp v122, v38, v202 row_shl:1 row_mask:0xf bank_mask:0xf bound_ctrl:1
	v_fmac_f32_dpp v123, v39, v203 row_shl:1 row_mask:0xf bank_mask:0xf bound_ctrl:1
	v_fmac_f32_dpp v116, v64, v220 row_shl:15 row_mask:0xf bank_mask:0xf bound_ctrl:1
	v_fmac_f32_dpp v117, v65, v221 row_shl:15 row_mask:0xf bank_mask:0xf bound_ctrl:1
	v_fmac_f32_dpp v118, v66, v222 row_shl:15 row_mask:0xf bank_mask:0xf bound_ctrl:1
	v_fmac_f32_dpp v119, v67, v223 row_shl:15 row_mask:0xf bank_mask:0xf bound_ctrl:1
	v_fmac_f32_dpp v120, v56, v204 row_shl:15 row_mask:0xf bank_mask:0xf bound_ctrl:1
	v_fmac_f32_dpp v121, v57, v205 row_shl:15 row_mask:0xf bank_mask:0xf bound_ctrl:1
	v_fmac_f32_dpp v122, v58, v206 row_shl:15 row_mask:0xf bank_mask:0xf bound_ctrl:1
	v_fmac_f32_dpp v123, v59, v207 row_shl:15 row_mask:0xf bank_mask:0xf bound_ctrl:1
	v_fmac_f32_dpp v116, v40, v216 row_shr:15 row_mask:0xf bank_mask:0xf bound_ctrl:1
	v_fmac_f32_dpp v117, v41, v217 row_shr:15 row_mask:0xf bank_mask:0xf bound_ctrl:1
	v_fmac_f32_dpp v118, v42, v218 row_shr:15 row_mask:0xf bank_mask:0xf bound_ctrl:1
	v_fmac_f32_dpp v119, v43, v219 row_shr:15 row_mask:0xf bank_mask:0xf bound_ctrl:1
	v_fmac_f32_dpp v120, v32, v200 row_shr:15 row_mask:0xf bank_mask:0xf bound_ctrl:1
	v_fmac_f32_dpp v121, v33, v201 row_shr:15 row_mask:0xf bank_mask:0xf bound_ctrl:1
	v_fmac_f32_dpp v122, v34, v202 row_shr:15 row_mask:0xf bank_mask:0xf bound_ctrl:1
	v_fmac_f32_dpp v123, v35, v203 row_shr:15 row_mask:0xf bank_mask:0xf bound_ctrl:1
	v_pk_mul_f32 v[48:49], v[116:117], s[0:1]
	v_pk_mul_f32 v[50:51], v[118:119], s[0:1]
	v_pk_mul_f32 v[52:53], v[116:117], v[120:121]
	v_pk_mul_f32 v[54:55], v[118:119], v[122:123]
	v_exp_f32_e32 v48, v48
	v_exp_f32_e32 v49, v49
	v_exp_f32_e32 v50, v50
	v_exp_f32_e32 v51, v51
	s_nop 0
	v_pk_add_f32 v[48:49], v[48:49], 1.0 op_sel_hi:[1,0]
	v_pk_add_f32 v[50:51], v[50:51], 1.0 op_sel_hi:[1,0]
	v_rcp_f32_e32 v48, v48
	v_rcp_f32_e32 v49, v49
	v_rcp_f32_e32 v50, v50
	v_rcp_f32_e32 v51, v51
	s_nop 0
	v_pk_mul_f32 v[52:53], v[52:53], v[48:49]
	v_pk_mul_f32 v[54:55], v[54:55], v[50:51]
	v_cvt_pk_bf16_f32 v252, v52, v53
	v_cvt_pk_bf16_f32 v253, v54, v55
	global_store_dwordx2 v[244:245], v[252:253], off offset:8
	v_lshl_add_u64 v[244:245], v[244:245], 0, s[2:3]
	v_mul_f32_e32 v116, v208, v40
	v_mul_f32_e32 v117, v209, v41
	v_mul_f32_e32 v118, v210, v42
	v_mul_f32_e32 v119, v211, v43
	v_mul_f32_e32 v120, v212, v32
	v_mul_f32_e32 v121, v213, v33
	v_mul_f32_e32 v122, v214, v34
	v_mul_f32_e32 v123, v215, v35
	v_fmac_f32_dpp v116, v40, v220 row_shr:1 row_mask:0xf bank_mask:0xf bound_ctrl:1
	v_fmac_f32_dpp v117, v41, v221 row_shr:1 row_mask:0xf bank_mask:0xf bound_ctrl:1
	v_fmac_f32_dpp v118, v42, v222 row_shr:1 row_mask:0xf bank_mask:0xf bound_ctrl:1
	v_fmac_f32_dpp v119, v43, v223 row_shr:1 row_mask:0xf bank_mask:0xf bound_ctrl:1
	v_fmac_f32_dpp v120, v32, v204 row_shr:1 row_mask:0xf bank_mask:0xf bound_ctrl:1
	v_fmac_f32_dpp v121, v33, v205 row_shr:1 row_mask:0xf bank_mask:0xf bound_ctrl:1
	v_fmac_f32_dpp v122, v34, v206 row_shr:1 row_mask:0xf bank_mask:0xf bound_ctrl:1
	v_fmac_f32_dpp v123, v35, v207 row_shr:1 row_mask:0xf bank_mask:0xf bound_ctrl:1
	v_fmac_f32_dpp v116, v40, v216 row_shl:1 row_mask:0xf bank_mask:0xf bound_ctrl:1
	v_fmac_f32_dpp v117, v41, v217 row_shl:1 row_mask:0xf bank_mask:0xf bound_ctrl:1
	v_fmac_f32_dpp v118, v42, v218 row_shl:1 row_mask:0xf bank_mask:0xf bound_ctrl:1
	v_fmac_f32_dpp v119, v43, v219 row_shl:1 row_mask:0xf bank_mask:0xf bound_ctrl:1
	v_fmac_f32_dpp v120, v32, v200 row_shl:1 row_mask:0xf bank_mask:0xf bound_ctrl:1
	v_fmac_f32_dpp v121, v33, v201 row_shl:1 row_mask:0xf bank_mask:0xf bound_ctrl:1
	v_fmac_f32_dpp v122, v34, v202 row_shl:1 row_mask:0xf bank_mask:0xf bound_ctrl:1
	v_fmac_f32_dpp v123, v35, v203 row_shl:1 row_mask:0xf bank_mask:0xf bound_ctrl:1
	v_fmac_f32_dpp v116, v44, v220 row_shl:15 row_mask:0xf bank_mask:0xf bound_ctrl:1
	v_fmac_f32_dpp v117, v45, v221 row_shl:15 row_mask:0xf bank_mask:0xf bound_ctrl:1
	v_fmac_f32_dpp v118, v46, v222 row_shl:15 row_mask:0xf bank_mask:0xf bound_ctrl:1
	v_fmac_f32_dpp v119, v47, v223 row_shl:15 row_mask:0xf bank_mask:0xf bound_ctrl:1
	v_fmac_f32_dpp v120, v36, v204 row_shl:15 row_mask:0xf bank_mask:0xf bound_ctrl:1
	v_fmac_f32_dpp v121, v37, v205 row_shl:15 row_mask:0xf bank_mask:0xf bound_ctrl:1
	v_fmac_f32_dpp v122, v38, v206 row_shl:15 row_mask:0xf bank_mask:0xf bound_ctrl:1
	v_fmac_f32_dpp v123, v39, v207 row_shl:15 row_mask:0xf bank_mask:0xf bound_ctrl:1
	v_pk_mul_f32 v[48:49], v[116:117], s[0:1]
	v_pk_mul_f32 v[50:51], v[118:119], s[0:1]
	v_pk_mul_f32 v[52:53], v[116:117], v[120:121]
	v_pk_mul_f32 v[54:55], v[118:119], v[122:123]
	v_exp_f32_e32 v48, v48
	v_exp_f32_e32 v49, v49
	v_exp_f32_e32 v50, v50
	v_exp_f32_e32 v51, v51
	v_cvt_pk_bf16_f32 v196, v40, v41
	v_cvt_pk_bf16_f32 v197, v42, v43
	v_cvt_pk_bf16_f32 v198, v32, v33
	v_cvt_pk_bf16_f32 v199, v34, v35
	v_pk_add_f32 v[48:49], v[48:49], 1.0 op_sel_hi:[1,0]
	v_pk_add_f32 v[50:51], v[50:51], 1.0 op_sel_hi:[1,0]
	v_rcp_f32_e32 v48, v48
	v_rcp_f32_e32 v49, v49
	v_rcp_f32_e32 v50, v50
	v_rcp_f32_e32 v51, v51
	s_nop 0
	v_pk_mul_f32 v[52:53], v[52:53], v[48:49]
	v_pk_mul_f32 v[54:55], v[54:55], v[50:51]
	v_cvt_pk_bf16_f32 v252, v52, v53
	v_cvt_pk_bf16_f32 v253, v54, v55
	s_and_saveexec_b64 vcc, s[8:9]
	global_store_dwordx2 v[244:245], v[252:253], off offset:8
	s_mov_b64 exec, vcc
	v_add_co_u32_e32 v250, vcc, 0xfffdf000, v250
	s_nop 1
	v_addc_co_u32_e32 v251, vcc, -1, v251, vcc
	v_add_co_u32_e32 v194, vcc, 0x1000, v250
	s_nop 1
	v_addc_co_u32_e32 v195, vcc, 0, v251, vcc
	s_and_saveexec_b64 vcc, s[14:15]
	global_store_dwordx2 v[250:251], v[196:197], off offset:8
	global_store_dwordx2 v[194:195], v[198:199], off offset:1544
	s_mov_b64 exec, vcc
	s_cmp_lg_u32 s83, 0
	s_cbranch_scc1 .Lup_done
	v_add_co_u32_e32 v244, vcc, 0xb0000, v246
	s_nop 1
	v_addc_co_u32_e32 v245, vcc, 0, v247, vcc
	v_add_co_u32_e32 v250, vcc, 0x16000, v248
	s_nop 1
	v_addc_co_u32_e32 v251, vcc, 0, v249, vcc
	v_add_co_u32_e32 v194, vcc, 0x1000, v250
	s_nop 1
	v_addc_co_u32_e32 v195, vcc, 0, v251, vcc
	v_mul_f32_e32 v116, v208, v28
	v_mul_f32_e32 v117, v209, v29
	v_mul_f32_e32 v118, v210, v30
	v_mul_f32_e32 v119, v211, v31
	v_mul_f32_e32 v120, v212, v20
	v_mul_f32_e32 v121, v213, v21
	v_mul_f32_e32 v122, v214, v22
	v_mul_f32_e32 v123, v215, v23
	v_fmac_f32_dpp v116, v28, v220 row_shr:1 row_mask:0xf bank_mask:0xf bound_ctrl:1
	v_fmac_f32_dpp v117, v29, v221 row_shr:1 row_mask:0xf bank_mask:0xf bound_ctrl:1
	v_fmac_f32_dpp v118, v30, v222 row_shr:1 row_mask:0xf bank_mask:0xf bound_ctrl:1
	v_fmac_f32_dpp v119, v31, v223 row_shr:1 row_mask:0xf bank_mask:0xf bound_ctrl:1
	v_fmac_f32_dpp v120, v20, v204 row_shr:1 row_mask:0xf bank_mask:0xf bound_ctrl:1
	v_fmac_f32_dpp v121, v21, v205 row_shr:1 row_mask:0xf bank_mask:0xf bound_ctrl:1
	v_fmac_f32_dpp v122, v22, v206 row_shr:1 row_mask:0xf bank_mask:0xf bound_ctrl:1
	v_fmac_f32_dpp v123, v23, v207 row_shr:1 row_mask:0xf bank_mask:0xf bound_ctrl:1
	v_fmac_f32_dpp v116, v28, v216 row_shl:1 row_mask:0xf bank_mask:0xf bound_ctrl:1
	v_fmac_f32_dpp v117, v29, v217 row_shl:1 row_mask:0xf bank_mask:0xf bound_ctrl:1
	v_fmac_f32_dpp v118, v30, v218 row_shl:1 row_mask:0xf bank_mask:0xf bound_ctrl:1
	v_fmac_f32_dpp v119, v31, v219 row_shl:1 row_mask:0xf bank_mask:0xf bound_ctrl:1
	v_fmac_f32_dpp v120, v20, v200 row_shl:1 row_mask:0xf bank_mask:0xf bound_ctrl:1
	v_fmac_f32_dpp v121, v21, v201 row_shl:1 row_mask:0xf bank_mask:0xf bound_ctrl:1
	v_fmac_f32_dpp v122, v22, v202 row_shl:1 row_mask:0xf bank_mask:0xf bound_ctrl:1
	v_fmac_f32_dpp v123, v23, v203 row_shl:1 row_mask:0xf bank_mask:0xf bound_ctrl:1
	v_fmac_f32_dpp v116, v24, v216 row_shr:15 row_mask:0xf bank_mask:0xf bound_ctrl:1
	v_fmac_f32_dpp v117, v25, v217 row_shr:15 row_mask:0xf bank_mask:0xf bound_ctrl:1
	v_fmac_f32_dpp v118, v26, v218 row_shr:15 row_mask:0xf bank_mask:0xf bound_ctrl:1
	v_fmac_f32_dpp v119, v27, v219 row_shr:15 row_mask:0xf bank_mask:0xf bound_ctrl:1
	v_fmac_f32_dpp v120, v16, v200 row_shr:15 row_mask:0xf bank_mask:0xf bound_ctrl:1
	v_fmac_f32_dpp v121, v17, v201 row_shr:15 row_mask:0xf bank_mask:0xf bound_ctrl:1
	v_fmac_f32_dpp v122, v18, v202 row_shr:15 row_mask:0xf bank_mask:0xf bound_ctrl:1
	v_fmac_f32_dpp v123, v19, v203 row_shr:15 row_mask:0xf bank_mask:0xf bound_ctrl:1
	v_pk_mul_f32 v[48:49], v[116:117], s[0:1]
	v_pk_mul_f32 v[50:51], v[118:119], s[0:1]
	v_pk_mul_f32 v[52:53], v[116:117], v[120:121]
	v_pk_mul_f32 v[54:55], v[118:119], v[122:123]
	v_exp_f32_e32 v48, v48
	v_exp_f32_e32 v49, v49
	v_exp_f32_e32 v50, v50
	v_exp_f32_e32 v51, v51
	v_cvt_pk_bf16_f32 v196, v28, v29
	v_cvt_pk_bf16_f32 v197, v30, v31
	v_cvt_pk_bf16_f32 v198, v20, v21
	v_cvt_pk_bf16_f32 v199, v22, v23
	v_pk_add_f32 v[48:49], v[48:49], 1.0 op_sel_hi:[1,0]
	v_pk_add_f32 v[50:51], v[50:51], 1.0 op_sel_hi:[1,0]
	v_rcp_f32_e32 v48, v48
	v_rcp_f32_e32 v49, v49
	v_rcp_f32_e32 v50, v50
	v_rcp_f32_e32 v51, v51
	s_nop 0
	v_pk_mul_f32 v[52:53], v[52:53], v[48:49]
	v_pk_mul_f32 v[54:55], v[54:55], v[50:51]
	v_cvt_pk_bf16_f32 v252, v52, v53
	v_cvt_pk_bf16_f32 v253, v54, v55
	s_and_saveexec_b64 vcc, s[10:11]
	global_store_dwordx2 v[244:245], v[252:253], off offset:8
	s_mov_b64 exec, vcc
	s_and_saveexec_b64 vcc, s[12:13]
	global_store_dwordx2 v[250:251], v[196:197], off offset:8
	global_store_dwordx2 v[194:195], v[198:199], off offset:1544
	s_mov_b64 exec, vcc
	v_lshl_add_u64 v[244:245], v[244:245], 0, s[2:3]
	v_mul_f32_e32 v116, v208, v24
	v_mul_f32_e32 v117, v209, v25
	v_mul_f32_e32 v118, v210, v26
	v_mul_f32_e32 v119, v211, v27
	v_mul_f32_e32 v120, v212, v16
	v_mul_f32_e32 v121, v213, v17
	v_mul_f32_e32 v122, v214, v18
	v_mul_f32_e32 v123, v215, v19
	v_fmac_f32_dpp v116, v24, v220 row_shr:1 row_mask:0xf bank_mask:0xf bound_ctrl:1
	v_fmac_f32_dpp v117, v25, v221 row_shr:1 row_mask:0xf bank_mask:0xf bound_ctrl:1
	v_fmac_f32_dpp v118, v26, v222 row_shr:1 row_mask:0xf bank_mask:0xf bound_ctrl:1
	v_fmac_f32_dpp v119, v27, v223 row_shr:1 row_mask:0xf bank_mask:0xf bound_ctrl:1
	v_fmac_f32_dpp v120, v16, v204 row_shr:1 row_mask:0xf bank_mask:0xf bound_ctrl:1
	v_fmac_f32_dpp v121, v17, v205 row_shr:1 row_mask:0xf bank_mask:0xf bound_ctrl:1
	v_fmac_f32_dpp v122, v18, v206 row_shr:1 row_mask:0xf bank_mask:0xf bound_ctrl:1
	v_fmac_f32_dpp v123, v19, v207 row_shr:1 row_mask:0xf bank_mask:0xf bound_ctrl:1
	v_fmac_f32_dpp v116, v24, v216 row_shl:1 row_mask:0xf bank_mask:0xf bound_ctrl:1
	v_fmac_f32_dpp v117, v25, v217 row_shl:1 row_mask:0xf bank_mask:0xf bound_ctrl:1
	v_fmac_f32_dpp v118, v26, v218 row_shl:1 row_mask:0xf bank_mask:0xf bound_ctrl:1
	v_fmac_f32_dpp v119, v27, v219 row_shl:1 row_mask:0xf bank_mask:0xf bound_ctrl:1
	v_fmac_f32_dpp v120, v16, v200 row_shl:1 row_mask:0xf bank_mask:0xf bound_ctrl:1
	v_fmac_f32_dpp v121, v17, v201 row_shl:1 row_mask:0xf bank_mask:0xf bound_ctrl:1
	v_fmac_f32_dpp v122, v18, v202 row_shl:1 row_mask:0xf bank_mask:0xf bound_ctrl:1
	v_fmac_f32_dpp v123, v19, v203 row_shl:1 row_mask:0xf bank_mask:0xf bound_ctrl:1
	v_fmac_f32_dpp v116, v28, v220 row_shl:15 row_mask:0xf bank_mask:0xf bound_ctrl:1
	v_fmac_f32_dpp v117, v29, v221 row_shl:15 row_mask:0xf bank_mask:0xf bound_ctrl:1
	v_fmac_f32_dpp v118, v30, v222 row_shl:15 row_mask:0xf bank_mask:0xf bound_ctrl:1
	v_fmac_f32_dpp v119, v31, v223 row_shl:15 row_mask:0xf bank_mask:0xf bound_ctrl:1
	v_fmac_f32_dpp v120, v20, v204 row_shl:15 row_mask:0xf bank_mask:0xf bound_ctrl:1
	v_fmac_f32_dpp v121, v21, v205 row_shl:15 row_mask:0xf bank_mask:0xf bound_ctrl:1
	v_fmac_f32_dpp v122, v22, v206 row_shl:15 row_mask:0xf bank_mask:0xf bound_ctrl:1
	v_fmac_f32_dpp v123, v23, v207 row_shl:15 row_mask:0xf bank_mask:0xf bound_ctrl:1
	v_fmac_f32_dpp v116, v12, v216 row_shr:15 row_mask:0xf bank_mask:0xf bound_ctrl:1
	v_fmac_f32_dpp v117, v13, v217 row_shr:15 row_mask:0xf bank_mask:0xf bound_ctrl:1
	v_fmac_f32_dpp v118, v14, v218 row_shr:15 row_mask:0xf bank_mask:0xf bound_ctrl:1
	v_fmac_f32_dpp v119, v15, v219 row_shr:15 row_mask:0xf bank_mask:0xf bound_ctrl:1
	v_fmac_f32_dpp v120, v4, v200 row_shr:15 row_mask:0xf bank_mask:0xf bound_ctrl:1
	v_fmac_f32_dpp v121, v5, v201 row_shr:15 row_mask:0xf bank_mask:0xf bound_ctrl:1
	v_fmac_f32_dpp v122, v6, v202 row_shr:15 row_mask:0xf bank_mask:0xf bound_ctrl:1
	v_fmac_f32_dpp v123, v7, v203 row_shr:15 row_mask:0xf bank_mask:0xf bound_ctrl:1
	v_pk_mul_f32 v[48:49], v[116:117], s[0:1]
	v_pk_mul_f32 v[50:51], v[118:119], s[0:1]
	v_pk_mul_f32 v[52:53], v[116:117], v[120:121]
	v_pk_mul_f32 v[54:55], v[118:119], v[122:123]
	v_exp_f32_e32 v48, v48
	v_exp_f32_e32 v49, v49
	v_exp_f32_e32 v50, v50
	v_exp_f32_e32 v51, v51
	s_nop 0
	v_pk_add_f32 v[48:49], v[48:49], 1.0 op_sel_hi:[1,0]
	v_pk_add_f32 v[50:51], v[50:51], 1.0 op_sel_hi:[1,0]
	v_rcp_f32_e32 v48, v48
	v_rcp_f32_e32 v49, v49
	v_rcp_f32_e32 v50, v50
	v_rcp_f32_e32 v51, v51
	s_nop 0
	v_pk_mul_f32 v[52:53], v[52:53], v[48:49]
	v_pk_mul_f32 v[54:55], v[54:55], v[50:51]
	v_cvt_pk_bf16_f32 v252, v52, v53
	v_cvt_pk_bf16_f32 v253, v54, v55
	global_store_dwordx2 v[244:245], v[252:253], off offset:8
	v_lshl_add_u64 v[244:245], v[244:245], 0, s[2:3]
	v_mul_f32_e32 v116, v208, v12
	v_mul_f32_e32 v117, v209, v13
	v_mul_f32_e32 v118, v210, v14
	v_mul_f32_e32 v119, v211, v15
	v_mul_f32_e32 v120, v212, v4
	v_mul_f32_e32 v121, v213, v5
	v_mul_f32_e32 v122, v214, v6
	v_mul_f32_e32 v123, v215, v7
	v_fmac_f32_dpp v116, v12, v220 row_shr:1 row_mask:0xf bank_mask:0xf bound_ctrl:1
	v_fmac_f32_dpp v117, v13, v221 row_shr:1 row_mask:0xf bank_mask:0xf bound_ctrl:1
	v_fmac_f32_dpp v118, v14, v222 row_shr:1 row_mask:0xf bank_mask:0xf bound_ctrl:1
	v_fmac_f32_dpp v119, v15, v223 row_shr:1 row_mask:0xf bank_mask:0xf bound_ctrl:1
	v_fmac_f32_dpp v120, v4, v204 row_shr:1 row_mask:0xf bank_mask:0xf bound_ctrl:1
	v_fmac_f32_dpp v121, v5, v205 row_shr:1 row_mask:0xf bank_mask:0xf bound_ctrl:1
	v_fmac_f32_dpp v122, v6, v206 row_shr:1 row_mask:0xf bank_mask:0xf bound_ctrl:1
	v_fmac_f32_dpp v123, v7, v207 row_shr:1 row_mask:0xf bank_mask:0xf bound_ctrl:1
	v_fmac_f32_dpp v116, v12, v216 row_shl:1 row_mask:0xf bank_mask:0xf bound_ctrl:1
	v_fmac_f32_dpp v117, v13, v217 row_shl:1 row_mask:0xf bank_mask:0xf bound_ctrl:1
	v_fmac_f32_dpp v118, v14, v218 row_shl:1 row_mask:0xf bank_mask:0xf bound_ctrl:1
	v_fmac_f32_dpp v119, v15, v219 row_shl:1 row_mask:0xf bank_mask:0xf bound_ctrl:1
	v_fmac_f32_dpp v120, v4, v200 row_shl:1 row_mask:0xf bank_mask:0xf bound_ctrl:1
	v_fmac_f32_dpp v121, v5, v201 row_shl:1 row_mask:0xf bank_mask:0xf bound_ctrl:1
	v_fmac_f32_dpp v122, v6, v202 row_shl:1 row_mask:0xf bank_mask:0xf bound_ctrl:1
	v_fmac_f32_dpp v123, v7, v203 row_shl:1 row_mask:0xf bank_mask:0xf bound_ctrl:1
	v_fmac_f32_dpp v116, v24, v220 row_shl:15 row_mask:0xf bank_mask:0xf bound_ctrl:1
	v_fmac_f32_dpp v117, v25, v221 row_shl:15 row_mask:0xf bank_mask:0xf bound_ctrl:1
	v_fmac_f32_dpp v118, v26, v222 row_shl:15 row_mask:0xf bank_mask:0xf bound_ctrl:1
	v_fmac_f32_dpp v119, v27, v223 row_shl:15 row_mask:0xf bank_mask:0xf bound_ctrl:1
	v_fmac_f32_dpp v120, v16, v204 row_shl:15 row_mask:0xf bank_mask:0xf bound_ctrl:1
	v_fmac_f32_dpp v121, v17, v205 row_shl:15 row_mask:0xf bank_mask:0xf bound_ctrl:1
	v_fmac_f32_dpp v122, v18, v206 row_shl:15 row_mask:0xf bank_mask:0xf bound_ctrl:1
	v_fmac_f32_dpp v123, v19, v207 row_shl:15 row_mask:0xf bank_mask:0xf bound_ctrl:1
	v_fmac_f32_dpp v116, v8, v216 row_shr:15 row_mask:0xf bank_mask:0xf bound_ctrl:1
	v_fmac_f32_dpp v117, v9, v217 row_shr:15 row_mask:0xf bank_mask:0xf bound_ctrl:1
	v_fmac_f32_dpp v118, v10, v218 row_shr:15 row_mask:0xf bank_mask:0xf bound_ctrl:1
	v_fmac_f32_dpp v119, v11, v219 row_shr:15 row_mask:0xf bank_mask:0xf bound_ctrl:1
	v_fmac_f32_dpp v120, v0, v200 row_shr:15 row_mask:0xf bank_mask:0xf bound_ctrl:1
	v_fmac_f32_dpp v121, v1, v201 row_shr:15 row_mask:0xf bank_mask:0xf bound_ctrl:1
	v_fmac_f32_dpp v122, v2, v202 row_shr:15 row_mask:0xf bank_mask:0xf bound_ctrl:1
	v_fmac_f32_dpp v123, v3, v203 row_shr:15 row_mask:0xf bank_mask:0xf bound_ctrl:1
	v_pk_mul_f32 v[48:49], v[116:117], s[0:1]
	v_pk_mul_f32 v[50:51], v[118:119], s[0:1]
	v_pk_mul_f32 v[52:53], v[116:117], v[120:121]
	v_pk_mul_f32 v[54:55], v[118:119], v[122:123]
	v_exp_f32_e32 v48, v48
	v_exp_f32_e32 v49, v49
	v_exp_f32_e32 v50, v50
	v_exp_f32_e32 v51, v51
	s_nop 0
	v_pk_add_f32 v[48:49], v[48:49], 1.0 op_sel_hi:[1,0]
	v_pk_add_f32 v[50:51], v[50:51], 1.0 op_sel_hi:[1,0]
	v_rcp_f32_e32 v48, v48
	v_rcp_f32_e32 v49, v49
	v_rcp_f32_e32 v50, v50
	v_rcp_f32_e32 v51, v51
	s_nop 0
	v_pk_mul_f32 v[52:53], v[52:53], v[48:49]
	v_pk_mul_f32 v[54:55], v[54:55], v[50:51]
	v_cvt_pk_bf16_f32 v252, v52, v53
	v_cvt_pk_bf16_f32 v253, v54, v55
	global_store_dwordx2 v[244:245], v[252:253], off offset:8
	v_lshl_add_u64 v[244:245], v[244:245], 0, s[2:3]
	v_mul_f32_e32 v116, v208, v8
	v_mul_f32_e32 v117, v209, v9
	v_mul_f32_e32 v118, v210, v10
	v_mul_f32_e32 v119, v211, v11
	v_mul_f32_e32 v120, v212, v0
	v_mul_f32_e32 v121, v213, v1
	v_mul_f32_e32 v122, v214, v2
	v_mul_f32_e32 v123, v215, v3
	v_fmac_f32_dpp v116, v8, v220 row_shr:1 row_mask:0xf bank_mask:0xf bound_ctrl:1
	v_fmac_f32_dpp v117, v9, v221 row_shr:1 row_mask:0xf bank_mask:0xf bound_ctrl:1
	v_fmac_f32_dpp v118, v10, v222 row_shr:1 row_mask:0xf bank_mask:0xf bound_ctrl:1
	v_fmac_f32_dpp v119, v11, v223 row_shr:1 row_mask:0xf bank_mask:0xf bound_ctrl:1
	v_fmac_f32_dpp v120, v0, v204 row_shr:1 row_mask:0xf bank_mask:0xf bound_ctrl:1
	v_fmac_f32_dpp v121, v1, v205 row_shr:1 row_mask:0xf bank_mask:0xf bound_ctrl:1
	v_fmac_f32_dpp v122, v2, v206 row_shr:1 row_mask:0xf bank_mask:0xf bound_ctrl:1
	v_fmac_f32_dpp v123, v3, v207 row_shr:1 row_mask:0xf bank_mask:0xf bound_ctrl:1
	v_fmac_f32_dpp v116, v8, v216 row_shl:1 row_mask:0xf bank_mask:0xf bound_ctrl:1
	v_fmac_f32_dpp v117, v9, v217 row_shl:1 row_mask:0xf bank_mask:0xf bound_ctrl:1
	v_fmac_f32_dpp v118, v10, v218 row_shl:1 row_mask:0xf bank_mask:0xf bound_ctrl:1
	v_fmac_f32_dpp v119, v11, v219 row_shl:1 row_mask:0xf bank_mask:0xf bound_ctrl:1
	v_fmac_f32_dpp v120, v0, v200 row_shl:1 row_mask:0xf bank_mask:0xf bound_ctrl:1
	v_fmac_f32_dpp v121, v1, v201 row_shl:1 row_mask:0xf bank_mask:0xf bound_ctrl:1
	v_fmac_f32_dpp v122, v2, v202 row_shl:1 row_mask:0xf bank_mask:0xf bound_ctrl:1
	v_fmac_f32_dpp v123, v3, v203 row_shl:1 row_mask:0xf bank_mask:0xf bound_ctrl:1
	v_fmac_f32_dpp v116, v12, v220 row_shl:15 row_mask:0xf bank_mask:0xf bound_ctrl:1
	v_fmac_f32_dpp v117, v13, v221 row_shl:15 row_mask:0xf bank_mask:0xf bound_ctrl:1
	v_fmac_f32_dpp v118, v14, v222 row_shl:15 row_mask:0xf bank_mask:0xf bound_ctrl:1
	v_fmac_f32_dpp v119, v15, v223 row_shl:15 row_mask:0xf bank_mask:0xf bound_ctrl:1
	v_fmac_f32_dpp v120, v4, v204 row_shl:15 row_mask:0xf bank_mask:0xf bound_ctrl:1
	v_fmac_f32_dpp v121, v5, v205 row_shl:15 row_mask:0xf bank_mask:0xf bound_ctrl:1
	v_fmac_f32_dpp v122, v6, v206 row_shl:15 row_mask:0xf bank_mask:0xf bound_ctrl:1
	v_fmac_f32_dpp v123, v7, v207 row_shl:15 row_mask:0xf bank_mask:0xf bound_ctrl:1
	v_pk_mul_f32 v[48:49], v[116:117], s[0:1]
	v_pk_mul_f32 v[50:51], v[118:119], s[0:1]
	v_pk_mul_f32 v[52:53], v[116:117], v[120:121]
	v_pk_mul_f32 v[54:55], v[118:119], v[122:123]
	v_exp_f32_e32 v48, v48
	v_exp_f32_e32 v49, v49
	v_exp_f32_e32 v50, v50
	v_exp_f32_e32 v51, v51
	v_cvt_pk_bf16_f32 v196, v8, v9
	v_cvt_pk_bf16_f32 v197, v10, v11
	v_cvt_pk_bf16_f32 v198, v0, v1
	v_cvt_pk_bf16_f32 v199, v2, v3
	v_pk_add_f32 v[48:49], v[48:49], 1.0 op_sel_hi:[1,0]
	v_pk_add_f32 v[50:51], v[50:51], 1.0 op_sel_hi:[1,0]
	v_rcp_f32_e32 v48, v48
	v_rcp_f32_e32 v49, v49
	v_rcp_f32_e32 v50, v50
	v_rcp_f32_e32 v51, v51
	s_nop 0
	v_pk_mul_f32 v[52:53], v[52:53], v[48:49]
	v_pk_mul_f32 v[54:55], v[54:55], v[50:51]
	v_cvt_pk_bf16_f32 v252, v52, v53
	v_cvt_pk_bf16_f32 v253, v54, v55
	s_and_saveexec_b64 vcc, s[8:9]
	global_store_dwordx2 v[244:245], v[252:253], off offset:8
	s_mov_b64 exec, vcc
	v_add_co_u32_e32 v250, vcc, 0xfffdf000, v250
	s_nop 1
	v_addc_co_u32_e32 v251, vcc, -1, v251, vcc
	v_add_co_u32_e32 v194, vcc, 0x1000, v250
	s_nop 1
	v_addc_co_u32_e32 v195, vcc, 0, v251, vcc
	s_and_saveexec_b64 vcc, s[14:15]
	global_store_dwordx2 v[250:251], v[196:197], off offset:8
	global_store_dwordx2 v[194:195], v[198:199], off offset:1544
	s_mov_b64 exec, vcc

.Lup_half_peel:
	s_add_u32 s2, s10, 0xfffc0080
	s_addc_u32 s3, s11, -1
	s_add_i32 s68, 0, 0x10000
	v_add_u32_e32 v108, s68, v237
	ds_read_b128 v[48:51], v108
	ds_read_b128 v[52:55], v108 offset:1024
	ds_read_b128 v[104:107], v108 offset:2048
	ds_read_b128 v[108:111], v108 offset:3072
	s_cmp_eq_u32 s67, 12
	s_cselect_b32 s13, s1, s3
	s_cselect_b32 s12, s9, s2
	s_cselect_b32 s3, s14, s39
	s_cselect_b32 s2, s15, s37
	v_lshl_add_u64 v[198:199], s[10:11], 0, v[186:187]
	s_add_i32 m0, s54, 0xc000
	ds_read_b128 v[112:115], v238
	ds_read_b128 v[116:119], v238 offset:1024
	ds_read_b128 v[120:123], v238 offset:2048
	ds_read_b128 v[156:159], v238 offset:3072
	ds_read_b128 v[160:163], v238 offset:4096
	ds_read_b128 v[164:167], v238 offset:5120
	ds_read_b128 v[190:193], v238 offset:6144
	ds_read_b128 v[194:197], v238 offset:7168
	global_load_lds_dwordx4 v[198:199], off
	v_lshl_add_u64 v[198:199], s[10:11], 0, v[188:189]
	s_add_i32 m0, s54, 0xe000
	s_nop 0
	global_load_lds_dwordx4 v[198:199], off
	s_waitcnt lgkmcnt(8)
	s_barrier
	s_waitcnt lgkmcnt(0)
	s_setprio 1
	s_waitcnt lgkmcnt(0)
	v_mfma_f32_16x16x32_bf16 v[152:155], v[48:51], v[112:115], 0
	v_mfma_f32_16x16x32_bf16 v[68:71], v[104:107], v[112:115], 0
	v_mfma_f32_16x16x32_bf16 v[148:151], v[48:51], v[120:123], 0
	v_mfma_f32_16x16x32_bf16 v[64:67], v[104:107], v[120:123], 0
	v_mfma_f32_16x16x32_bf16 v[136:139], v[48:51], v[160:163], 0
	v_mfma_f32_16x16x32_bf16 v[44:47], v[104:107], v[160:163], 0
	v_mfma_f32_16x16x32_bf16 v[128:131], v[48:51], v[190:193], 0
	v_mfma_f32_16x16x32_bf16 v[40:43], v[104:107], v[190:193], 0
	v_mfma_f32_16x16x32_bf16 v[152:155], v[52:55], v[116:119], v[152:155]
	v_mfma_f32_16x16x32_bf16 v[68:71], v[108:111], v[116:119], v[68:71]
	v_mfma_f32_16x16x32_bf16 v[148:151], v[52:55], v[156:159], v[148:151]
	v_mfma_f32_16x16x32_bf16 v[64:67], v[108:111], v[156:159], v[64:67]
	v_mfma_f32_16x16x32_bf16 v[136:139], v[52:55], v[164:167], v[136:139]
	v_mfma_f32_16x16x32_bf16 v[44:47], v[108:111], v[164:167], v[44:47]
	v_mfma_f32_16x16x32_bf16 v[128:131], v[52:55], v[194:197], v[128:131]
	v_mfma_f32_16x16x32_bf16 v[40:43], v[108:111], v[194:197], v[40:43]
	s_setprio 0
	s_barrier
	s_add_i32 s70, 0, 0x14000
	s_add_i32 s68, s68, s53
	v_add_u32_e32 v210, s70, v237
	v_lshl_add_u64 v[218:219], s[2:3], 0, v[168:169]
	s_mov_b32 m0, s68
	ds_read_b128 v[198:201], v210
	ds_read_b128 v[202:205], v210 offset:1024
	ds_read_b128 v[206:209], v210 offset:2048
	ds_read_b128 v[210:213], v210 offset:3072
	global_load_lds_dwordx4 v[218:219], off
	v_lshl_add_u64 v[220:221], s[2:3], 0, v[184:185]
	s_add_i32 m0, s68, 0x2000
	s_nop 0
	global_load_lds_dwordx4 v[220:221], off
	s_barrier
	s_waitcnt lgkmcnt(0)
	s_setprio 1
	s_waitcnt lgkmcnt(0)
	v_mfma_f32_16x16x32_bf16 v[144:147], v[198:201], v[112:115], 0
	v_mfma_f32_16x16x32_bf16 v[60:63], v[206:209], v[112:115], 0
	v_mfma_f32_16x16x32_bf16 v[56:59], v[206:209], v[120:123], 0
	v_mfma_f32_16x16x32_bf16 v[36:39], v[206:209], v[160:163], 0
	v_mfma_f32_16x16x32_bf16 v[32:35], v[206:209], v[190:193], 0
	v_mfma_f32_16x16x32_bf16 v[144:147], v[202:205], v[116:119], v[144:147]
	v_mfma_f32_16x16x32_bf16 v[60:63], v[210:213], v[116:119], v[60:63]
	v_mfma_f32_16x16x32_bf16 v[112:115], v[198:201], v[120:123], 0
	v_mfma_f32_16x16x32_bf16 v[56:59], v[210:213], v[156:159], v[56:59]
	v_mfma_f32_16x16x32_bf16 v[116:119], v[198:201], v[160:163], 0
	v_mfma_f32_16x16x32_bf16 v[36:39], v[210:213], v[164:167], v[36:39]
	v_mfma_f32_16x16x32_bf16 v[120:123], v[198:201], v[190:193], 0
	v_mfma_f32_16x16x32_bf16 v[32:35], v[210:213], v[194:197], v[32:35]
	v_mfma_f32_16x16x32_bf16 v[112:115], v[202:205], v[156:159], v[112:115]
	v_mfma_f32_16x16x32_bf16 v[116:119], v[202:205], v[164:167], v[116:119]
	v_mfma_f32_16x16x32_bf16 v[120:123], v[202:205], v[194:197], v[120:123]
	s_setprio 0
	s_mov_b32 m0, s54
	v_lshl_add_u64 v[222:223], s[12:13], 0, v[180:181]
	s_barrier
	ds_read_b128 v[124:127], v238 offset:16384
	ds_read_b128 v[132:135], v238 offset:17408
	ds_read_b128 v[140:143], v238 offset:18432
	ds_read_b128 v[156:159], v238 offset:19456
	ds_read_b128 v[160:163], v238 offset:20480
	ds_read_b128 v[164:167], v238 offset:21504
	ds_read_b128 v[190:193], v238 offset:22528
	ds_read_b128 v[194:197], v238 offset:23552
	global_load_lds_dwordx4 v[222:223], off
	v_lshl_add_u64 v[240:241], s[12:13], 0, v[182:183]
	s_mov_b32 m0, s55
	s_nop 0
	global_load_lds_dwordx4 v[240:241], off
	s_barrier
	s_waitcnt lgkmcnt(0)
	s_setprio 1
	s_waitcnt lgkmcnt(0)
	s_setprio 0
	s_barrier
	s_add_u32 s68, s2, 0x40000
	s_addc_u32 s69, s3, 0
	s_add_i32 s70, s70, s53
	v_lshl_add_u64 v[52:53], s[68:69], 0, v[168:169]
	s_mov_b32 m0, s70
	s_nop 0
	global_load_lds_dwordx4 v[52:53], off
	v_lshl_add_u64 v[52:53], s[68:69], 0, v[184:185]
	s_add_i32 m0, s70, 0x2000
	s_nop 0
	global_load_lds_dwordx4 v[52:53], off
	s_waitcnt vmcnt(6)
	s_barrier
	s_setprio 1
	s_setprio 0
	s_add_i32 s68, 0, 0x18000
	v_add_u32_e32 v108, s68, v237
	s_barrier
	ds_read_b128 v[76:79], v108
	ds_read_b128 v[92:95], v108 offset:1024
	ds_read_b128 v[104:107], v108 offset:2048
	ds_read_b128 v[108:111], v108 offset:3072
	s_add_u32 s12, s12, 0x40000
	s_addc_u32 s13, s13, 0
	s_mov_b32 m0, s56
	v_lshl_add_u64 v[140:141], s[12:13], 0, v[180:181]
	ds_read_b128 v[124:127], v238 offset:32768
	ds_read_b128 v[132:135], v238 offset:33792
	ds_read_b128 v[156:159], v238 offset:34816
	ds_read_b128 v[160:163], v238 offset:35840
	ds_read_b128 v[164:167], v238 offset:36864
	ds_read_b128 v[190:193], v238 offset:37888
	ds_read_b128 v[194:197], v238 offset:38912
	ds_read_b128 v[198:201], v238 offset:39936
	global_load_lds_dwordx4 v[140:141], off
	v_lshl_add_u64 v[140:141], s[12:13], 0, v[182:183]
	s_mov_b32 m0, s57
	s_nop 0
	global_load_lds_dwordx4 v[140:141], off
	s_waitcnt lgkmcnt(8)
	s_barrier
	s_waitcnt lgkmcnt(0)
	s_setprio 1
	s_waitcnt lgkmcnt(0)
	v_mfma_f32_16x16x32_bf16 v[140:143], v[76:79], v[124:127], v[152:155]
	v_mfma_f32_16x16x32_bf16 v[152:155], v[92:95], v[132:135], v[140:143]
	v_mfma_f32_16x16x32_bf16 v[68:71], v[104:107], v[124:127], v[68:71]
	v_mfma_f32_16x16x32_bf16 v[140:143], v[76:79], v[156:159], v[148:151]
	v_mfma_f32_16x16x32_bf16 v[64:67], v[104:107], v[156:159], v[64:67]
	v_mfma_f32_16x16x32_bf16 v[136:139], v[76:79], v[164:167], v[136:139]
	v_mfma_f32_16x16x32_bf16 v[44:47], v[104:107], v[164:167], v[44:47]
	v_mfma_f32_16x16x32_bf16 v[128:131], v[76:79], v[194:197], v[128:131]
	v_mfma_f32_16x16x32_bf16 v[40:43], v[104:107], v[194:197], v[40:43]
	v_mfma_f32_16x16x32_bf16 v[68:71], v[108:111], v[132:135], v[68:71]
	v_mfma_f32_16x16x32_bf16 v[148:151], v[92:95], v[160:163], v[140:143]
	v_mfma_f32_16x16x32_bf16 v[64:67], v[108:111], v[160:163], v[64:67]
	v_mfma_f32_16x16x32_bf16 v[136:139], v[92:95], v[190:193], v[136:139]
	v_mfma_f32_16x16x32_bf16 v[44:47], v[108:111], v[190:193], v[44:47]
	v_mfma_f32_16x16x32_bf16 v[128:131], v[92:95], v[198:201], v[128:131]
	v_mfma_f32_16x16x32_bf16 v[40:43], v[108:111], v[198:201], v[40:43]
	s_setprio 0
	s_barrier
	s_add_i32 s12, 0, 0x1c000
	v_add_u32_e32 v140, s12, v237
	s_add_i32 s13, s68, s53
	ds_read_b128 v[202:205], v140
	ds_read_b128 v[206:209], v140 offset:1024
	ds_read_b128 v[210:213], v140 offset:2048
	ds_read_b128 v[214:217], v140 offset:3072
	v_lshl_add_u64 v[140:141], v[218:219], 0, s[78:79]
	s_mov_b32 m0, s13
	s_nop 0
	global_load_lds_dwordx4 v[140:141], off
	v_lshl_add_u64 v[140:141], v[220:221], 0, s[78:79]
	s_add_i32 m0, s13, 0x2000
	s_nop 0
	global_load_lds_dwordx4 v[140:141], off
	s_barrier
	s_waitcnt lgkmcnt(0)
	s_setprio 1
	s_waitcnt lgkmcnt(0)
	v_mfma_f32_16x16x32_bf16 v[140:143], v[202:205], v[124:127], v[144:147]
	v_mfma_f32_16x16x32_bf16 v[112:115], v[202:205], v[156:159], v[112:115]
	v_mfma_f32_16x16x32_bf16 v[144:147], v[206:209], v[132:135], v[140:143]
	v_mfma_f32_16x16x32_bf16 v[60:63], v[210:213], v[124:127], v[60:63]
	v_mfma_f32_16x16x32_bf16 v[140:143], v[206:209], v[160:163], v[112:115]
	v_mfma_f32_16x16x32_bf16 v[112:115], v[202:205], v[164:167], v[116:119]
	v_mfma_f32_16x16x32_bf16 v[60:63], v[214:217], v[132:135], v[60:63]
	v_mfma_f32_16x16x32_bf16 v[56:59], v[210:213], v[156:159], v[56:59]
	v_mfma_f32_16x16x32_bf16 v[132:135], v[206:209], v[190:193], v[112:115]
	v_mfma_f32_16x16x32_bf16 v[36:39], v[210:213], v[164:167], v[36:39]
	v_mfma_f32_16x16x32_bf16 v[112:115], v[202:205], v[194:197], v[120:123]
	v_mfma_f32_16x16x32_bf16 v[32:35], v[210:213], v[194:197], v[32:35]
	v_mfma_f32_16x16x32_bf16 v[56:59], v[214:217], v[160:163], v[56:59]
	v_mfma_f32_16x16x32_bf16 v[36:39], v[214:217], v[190:193], v[36:39]
	v_mfma_f32_16x16x32_bf16 v[124:127], v[206:209], v[198:201], v[112:115]
	v_mfma_f32_16x16x32_bf16 v[32:35], v[214:217], v[198:201], v[32:35]
	s_setprio 0
	s_mov_b32 m0, s62
	v_lshl_add_u64 v[198:199], v[222:223], 0, s[78:79]
	s_barrier
	ds_read_b128 v[112:115], v238 offset:49152
	ds_read_b128 v[116:119], v238 offset:50176
	ds_read_b128 v[120:123], v238 offset:51200
	ds_read_b128 v[156:159], v238 offset:52224
	ds_read_b128 v[160:163], v238 offset:53248
	ds_read_b128 v[164:167], v238 offset:54272
	ds_read_b128 v[190:193], v238 offset:55296
	ds_read_b128 v[194:197], v238 offset:56320
	global_load_lds_dwordx4 v[198:199], off
	v_lshl_add_u64 v[198:199], v[240:241], 0, s[78:79]
	s_mov_b32 m0, s63
	s_nop 0
	global_load_lds_dwordx4 v[198:199], off
	s_barrier
	s_waitcnt lgkmcnt(0)
	s_setprio 1
	s_waitcnt lgkmcnt(0)
	s_setprio 0
	s_barrier
	s_add_u32 s2, s2, 0x40080
	s_addc_u32 s3, s3, 0
	s_add_i32 s12, s12, s53
	v_lshl_add_u64 v[48:49], s[2:3], 0, v[168:169]
	s_mov_b32 m0, s12
	s_nop 0
	global_load_lds_dwordx4 v[48:49], off
	v_lshl_add_u64 v[48:49], s[2:3], 0, v[184:185]
	s_add_i32 m0, s12, 0x2000
	s_nop 0
	global_load_lds_dwordx4 v[48:49], off
	s_waitcnt vmcnt(6)
	s_barrier
	s_setprio 1
	s_setprio 0
	s_add_i32 s67, s67, 2
	s_add_u32 s10, s10, 0x100
	s_addc_u32 s11, s11, 0
	s_add_u32 s37, s37, 0x100
	s_addc_u32 s39, s39, 0
	s_cmp_gt_u32 s67, 13
	s_barrier
.Lup_half_loop:
	s_add_u32 s2, s10, 0xfffc0080
	s_addc_u32 s3, s11, -1
	s_add_i32 s68, 0, 0x10000
	v_add_u32_e32 v108, s68, v237
	ds_read_b128 v[48:51], v108
	ds_read_b128 v[52:55], v108 offset:1024
	ds_read_b128 v[104:107], v108 offset:2048
	ds_read_b128 v[108:111], v108 offset:3072
	s_cmp_eq_u32 s67, 12
	s_cselect_b32 s13, s1, s3
	s_cselect_b32 s12, s9, s2
	s_cselect_b32 s3, s14, s39
	s_cselect_b32 s2, s15, s37
	v_lshl_add_u64 v[198:199], s[10:11], 0, v[186:187]
	s_add_i32 m0, s54, 0xc000
	ds_read_b128 v[112:115], v238
	ds_read_b128 v[116:119], v238 offset:1024
	ds_read_b128 v[120:123], v238 offset:2048
	ds_read_b128 v[156:159], v238 offset:3072
	ds_read_b128 v[160:163], v238 offset:4096
	ds_read_b128 v[164:167], v238 offset:5120
	ds_read_b128 v[190:193], v238 offset:6144
	ds_read_b128 v[194:197], v238 offset:7168
	global_load_lds_dwordx4 v[198:199], off
	v_lshl_add_u64 v[198:199], s[10:11], 0, v[188:189]
	s_add_i32 m0, s54, 0xe000
	s_nop 0
	global_load_lds_dwordx4 v[198:199], off
	s_waitcnt lgkmcnt(8)
	s_barrier
	s_waitcnt lgkmcnt(0)
	s_setprio 1
	s_waitcnt lgkmcnt(0)
	v_mfma_f32_16x16x32_bf16 v[152:155], v[48:51], v[112:115], v[152:155]
	v_mfma_f32_16x16x32_bf16 v[68:71], v[104:107], v[112:115], v[68:71]
	v_mfma_f32_16x16x32_bf16 v[148:151], v[48:51], v[120:123], v[148:151]
	v_mfma_f32_16x16x32_bf16 v[64:67], v[104:107], v[120:123], v[64:67]
	v_mfma_f32_16x16x32_bf16 v[136:139], v[48:51], v[160:163], v[136:139]
	v_mfma_f32_16x16x32_bf16 v[44:47], v[104:107], v[160:163], v[44:47]
	v_mfma_f32_16x16x32_bf16 v[128:131], v[48:51], v[190:193], v[128:131]
	v_mfma_f32_16x16x32_bf16 v[40:43], v[104:107], v[190:193], v[40:43]
	v_mfma_f32_16x16x32_bf16 v[152:155], v[52:55], v[116:119], v[152:155]
	v_mfma_f32_16x16x32_bf16 v[68:71], v[108:111], v[116:119], v[68:71]
	v_mfma_f32_16x16x32_bf16 v[148:151], v[52:55], v[156:159], v[148:151]
	v_mfma_f32_16x16x32_bf16 v[64:67], v[108:111], v[156:159], v[64:67]
	v_mfma_f32_16x16x32_bf16 v[136:139], v[52:55], v[164:167], v[136:139]
	v_mfma_f32_16x16x32_bf16 v[44:47], v[108:111], v[164:167], v[44:47]
	v_mfma_f32_16x16x32_bf16 v[128:131], v[52:55], v[194:197], v[128:131]
	v_mfma_f32_16x16x32_bf16 v[40:43], v[108:111], v[194:197], v[40:43]
	s_setprio 0
	s_barrier
	s_add_i32 s70, 0, 0x14000
	s_add_i32 s68, s68, s53
	v_add_u32_e32 v210, s70, v237
	v_lshl_add_u64 v[218:219], s[2:3], 0, v[168:169]
	s_mov_b32 m0, s68
	ds_read_b128 v[198:201], v210
	ds_read_b128 v[202:205], v210 offset:1024
	ds_read_b128 v[206:209], v210 offset:2048
	ds_read_b128 v[210:213], v210 offset:3072
	global_load_lds_dwordx4 v[218:219], off
	v_lshl_add_u64 v[220:221], s[2:3], 0, v[184:185]
	s_add_i32 m0, s68, 0x2000
	s_nop 0
	global_load_lds_dwordx4 v[220:221], off
	s_barrier
	s_waitcnt lgkmcnt(0)
	s_setprio 1
	s_waitcnt lgkmcnt(0)
	v_mfma_f32_16x16x32_bf16 v[144:147], v[198:201], v[112:115], v[144:147]
	v_mfma_f32_16x16x32_bf16 v[60:63], v[206:209], v[112:115], v[60:63]
	v_mfma_f32_16x16x32_bf16 v[56:59], v[206:209], v[120:123], v[56:59]
	v_mfma_f32_16x16x32_bf16 v[36:39], v[206:209], v[160:163], v[36:39]
	v_mfma_f32_16x16x32_bf16 v[32:35], v[206:209], v[190:193], v[32:35]
	v_mfma_f32_16x16x32_bf16 v[144:147], v[202:205], v[116:119], v[144:147]
	v_mfma_f32_16x16x32_bf16 v[60:63], v[210:213], v[116:119], v[60:63]
	v_mfma_f32_16x16x32_bf16 v[112:115], v[198:201], v[120:123], v[140:143]
	v_mfma_f32_16x16x32_bf16 v[56:59], v[210:213], v[156:159], v[56:59]
	v_mfma_f32_16x16x32_bf16 v[116:119], v[198:201], v[160:163], v[132:135]
	v_mfma_f32_16x16x32_bf16 v[36:39], v[210:213], v[164:167], v[36:39]
	v_mfma_f32_16x16x32_bf16 v[120:123], v[198:201], v[190:193], v[124:127]
	v_mfma_f32_16x16x32_bf16 v[32:35], v[210:213], v[194:197], v[32:35]
	v_mfma_f32_16x16x32_bf16 v[112:115], v[202:205], v[156:159], v[112:115]
	v_mfma_f32_16x16x32_bf16 v[116:119], v[202:205], v[164:167], v[116:119]
	v_mfma_f32_16x16x32_bf16 v[120:123], v[202:205], v[194:197], v[120:123]
	s_setprio 0
	s_mov_b32 m0, s54
	v_lshl_add_u64 v[222:223], s[12:13], 0, v[180:181]
	s_barrier
	ds_read_b128 v[124:127], v238 offset:16384
	ds_read_b128 v[132:135], v238 offset:17408
	ds_read_b128 v[140:143], v238 offset:18432
	ds_read_b128 v[156:159], v238 offset:19456
	ds_read_b128 v[160:163], v238 offset:20480
	ds_read_b128 v[164:167], v238 offset:21504
	ds_read_b128 v[190:193], v238 offset:22528
	ds_read_b128 v[194:197], v238 offset:23552
	global_load_lds_dwordx4 v[222:223], off
	v_lshl_add_u64 v[240:241], s[12:13], 0, v[182:183]
	s_mov_b32 m0, s55
	s_nop 0
	global_load_lds_dwordx4 v[240:241], off
	s_barrier
	s_waitcnt lgkmcnt(0)
	s_setprio 1
	s_waitcnt lgkmcnt(0)
	s_setprio 0
	s_barrier
	s_add_u32 s68, s2, 0x40000
	s_addc_u32 s69, s3, 0
	s_add_i32 s70, s70, s53
	v_lshl_add_u64 v[52:53], s[68:69], 0, v[168:169]
	s_mov_b32 m0, s70
	s_nop 0
	global_load_lds_dwordx4 v[52:53], off
	v_lshl_add_u64 v[52:53], s[68:69], 0, v[184:185]
	s_add_i32 m0, s70, 0x2000
	s_nop 0
	global_load_lds_dwordx4 v[52:53], off
	s_waitcnt vmcnt(6)
	s_barrier
	s_setprio 1
	s_setprio 0
	s_add_i32 s68, 0, 0x18000
	v_add_u32_e32 v108, s68, v237
	s_barrier
	ds_read_b128 v[76:79], v108
	ds_read_b128 v[92:95], v108 offset:1024
	ds_read_b128 v[104:107], v108 offset:2048
	ds_read_b128 v[108:111], v108 offset:3072
	s_add_u32 s12, s12, 0x40000
	s_addc_u32 s13, s13, 0
	s_mov_b32 m0, s56
	v_lshl_add_u64 v[140:141], s[12:13], 0, v[180:181]
	ds_read_b128 v[124:127], v238 offset:32768
	ds_read_b128 v[132:135], v238 offset:33792
	ds_read_b128 v[156:159], v238 offset:34816
	ds_read_b128 v[160:163], v238 offset:35840
	ds_read_b128 v[164:167], v238 offset:36864
	ds_read_b128 v[190:193], v238 offset:37888
	ds_read_b128 v[194:197], v238 offset:38912
	ds_read_b128 v[198:201], v238 offset:39936
	global_load_lds_dwordx4 v[140:141], off
	v_lshl_add_u64 v[140:141], s[12:13], 0, v[182:183]
	s_mov_b32 m0, s57
	s_nop 0
	global_load_lds_dwordx4 v[140:141], off
	s_waitcnt lgkmcnt(8)
	s_barrier
	s_waitcnt lgkmcnt(0)
	s_setprio 1
	s_waitcnt lgkmcnt(0)
	v_mfma_f32_16x16x32_bf16 v[140:143], v[76:79], v[124:127], v[152:155]
	v_mfma_f32_16x16x32_bf16 v[152:155], v[92:95], v[132:135], v[140:143]
	v_mfma_f32_16x16x32_bf16 v[68:71], v[104:107], v[124:127], v[68:71]
	v_mfma_f32_16x16x32_bf16 v[140:143], v[76:79], v[156:159], v[148:151]
	v_mfma_f32_16x16x32_bf16 v[64:67], v[104:107], v[156:159], v[64:67]
	v_mfma_f32_16x16x32_bf16 v[136:139], v[76:79], v[164:167], v[136:139]
	v_mfma_f32_16x16x32_bf16 v[44:47], v[104:107], v[164:167], v[44:47]
	v_mfma_f32_16x16x32_bf16 v[128:131], v[76:79], v[194:197], v[128:131]
	v_mfma_f32_16x16x32_bf16 v[40:43], v[104:107], v[194:197], v[40:43]
	v_mfma_f32_16x16x32_bf16 v[68:71], v[108:111], v[132:135], v[68:71]
	v_mfma_f32_16x16x32_bf16 v[148:151], v[92:95], v[160:163], v[140:143]
	v_mfma_f32_16x16x32_bf16 v[64:67], v[108:111], v[160:163], v[64:67]
	v_mfma_f32_16x16x32_bf16 v[136:139], v[92:95], v[190:193], v[136:139]
	v_mfma_f32_16x16x32_bf16 v[44:47], v[108:111], v[190:193], v[44:47]
	v_mfma_f32_16x16x32_bf16 v[128:131], v[92:95], v[198:201], v[128:131]
	v_mfma_f32_16x16x32_bf16 v[40:43], v[108:111], v[198:201], v[40:43]
	s_setprio 0
	s_barrier
	s_add_i32 s12, 0, 0x1c000
	v_add_u32_e32 v140, s12, v237
	s_add_i32 s13, s68, s53
	ds_read_b128 v[202:205], v140
	ds_read_b128 v[206:209], v140 offset:1024
	ds_read_b128 v[210:213], v140 offset:2048
	ds_read_b128 v[214:217], v140 offset:3072
	v_lshl_add_u64 v[140:141], v[218:219], 0, s[78:79]
	s_mov_b32 m0, s13
	s_nop 0
	global_load_lds_dwordx4 v[140:141], off
	v_lshl_add_u64 v[140:141], v[220:221], 0, s[78:79]
	s_add_i32 m0, s13, 0x2000
	s_nop 0
	global_load_lds_dwordx4 v[140:141], off
	s_barrier
	s_waitcnt lgkmcnt(0)
	s_setprio 1
	s_waitcnt lgkmcnt(0)
	v_mfma_f32_16x16x32_bf16 v[140:143], v[202:205], v[124:127], v[144:147]
	v_mfma_f32_16x16x32_bf16 v[112:115], v[202:205], v[156:159], v[112:115]
	v_mfma_f32_16x16x32_bf16 v[144:147], v[206:209], v[132:135], v[140:143]
	v_mfma_f32_16x16x32_bf16 v[60:63], v[210:213], v[124:127], v[60:63]
	v_mfma_f32_16x16x32_bf16 v[140:143], v[206:209], v[160:163], v[112:115]
	v_mfma_f32_16x16x32_bf16 v[112:115], v[202:205], v[164:167], v[116:119]
	v_mfma_f32_16x16x32_bf16 v[60:63], v[214:217], v[132:135], v[60:63]
	v_mfma_f32_16x16x32_bf16 v[56:59], v[210:213], v[156:159], v[56:59]
	v_mfma_f32_16x16x32_bf16 v[132:135], v[206:209], v[190:193], v[112:115]
	v_mfma_f32_16x16x32_bf16 v[36:39], v[210:213], v[164:167], v[36:39]
	v_mfma_f32_16x16x32_bf16 v[112:115], v[202:205], v[194:197], v[120:123]
	v_mfma_f32_16x16x32_bf16 v[32:35], v[210:213], v[194:197], v[32:35]
	v_mfma_f32_16x16x32_bf16 v[56:59], v[214:217], v[160:163], v[56:59]
	v_mfma_f32_16x16x32_bf16 v[36:39], v[214:217], v[190:193], v[36:39]
	v_mfma_f32_16x16x32_bf16 v[124:127], v[206:209], v[198:201], v[112:115]
	v_mfma_f32_16x16x32_bf16 v[32:35], v[214:217], v[198:201], v[32:35]
	s_setprio 0
	s_mov_b32 m0, s62
	v_lshl_add_u64 v[198:199], v[222:223], 0, s[78:79]
	s_barrier
	ds_read_b128 v[112:115], v238 offset:49152
	ds_read_b128 v[116:119], v238 offset:50176
	ds_read_b128 v[120:123], v238 offset:51200
	ds_read_b128 v[156:159], v238 offset:52224
	ds_read_b128 v[160:163], v238 offset:53248
	ds_read_b128 v[164:167], v238 offset:54272
	ds_read_b128 v[190:193], v238 offset:55296
	ds_read_b128 v[194:197], v238 offset:56320
	global_load_lds_dwordx4 v[198:199], off
	v_lshl_add_u64 v[198:199], v[240:241], 0, s[78:79]
	s_mov_b32 m0, s63
	s_nop 0
	global_load_lds_dwordx4 v[198:199], off
	s_barrier
	s_waitcnt lgkmcnt(0)
	s_setprio 1
	s_waitcnt lgkmcnt(0)
	s_setprio 0
	s_barrier
	s_add_u32 s2, s2, 0x40080
	s_addc_u32 s3, s3, 0
	s_add_i32 s12, s12, s53
	v_lshl_add_u64 v[48:49], s[2:3], 0, v[168:169]
	s_mov_b32 m0, s12
	s_nop 0
	global_load_lds_dwordx4 v[48:49], off
	v_lshl_add_u64 v[48:49], s[2:3], 0, v[184:185]
	s_add_i32 m0, s12, 0x2000
	s_nop 0
	global_load_lds_dwordx4 v[48:49], off
	s_waitcnt vmcnt(6)
	s_barrier
	s_setprio 1
	s_setprio 0
	s_add_i32 s67, s67, 2
	s_add_u32 s10, s10, 0x100
	s_addc_u32 s11, s11, 0
	s_add_u32 s37, s37, 0x100
	s_addc_u32 s39, s39, 0
	s_cmp_gt_u32 s67, 13
	s_barrier
	s_cbranch_scc0 .Lup_half_loop
	s_branch .Lup_epi

.LBB0_923:
	v_readlane_b32 s0, v254, 0
	s_cmpk_lt_u32 s0, 0x40
	s_cbranch_scc1 .LBB0_964
	s_and_saveexec_b64 s[0:1], s[6:7]
	s_cbranch_execz .LBB0_927
	s_mov_b64 s[10:11], exec
	v_mbcnt_lo_u32_b32 v2, s10, 0
	v_mbcnt_hi_u32_b32 v2, s11, v2
	v_cmp_eq_u32_e32 vcc, 0, v2
	s_and_saveexec_b64 s[2:3], vcc
	s_cbranch_execz .LBB0_926
	s_bcnt1_i32_b64 s10, s[10:11]
	v_mov_b32_e32 v3, s10
	global_atomic_add v3, v169, v3, s[12:13] sc0

.LBB0_1176:
	v_readlane_b32 s2, v254, 0
	s_cmpk_lt_u32 s2, 0xc0
	s_cbranch_scc1 .LBB0_1193
	s_and_saveexec_b64 s[2:3], s[4:5]
	s_cbranch_execz .LBB0_1180
	s_mov_b64 s[12:13], exec
	v_mbcnt_lo_u32_b32 v0, s12, 0
	v_mbcnt_hi_u32_b32 v0, s13, v0
	v_cmp_eq_u32_e32 vcc, 0, v0
	s_and_saveexec_b64 s[8:9], vcc
	s_cbranch_execz .LBB0_1179
	s_bcnt1_i32_b64 s12, s[12:13]
	v_mov_b32_e32 v1, s12
	global_atomic_add v1, v169, v1, s[0:1] sc0
